# LDS transposed read-back of the P0/P2 weight-copy tiles issued 8 reads at a time (conflict-free after the row permutation) instead of pair/wait/cvt
# speedup vs baseline: 1.0004x; 1.0004x over previous
; #define GAS __attribute__((address_space(1)))
; #define LAS __attribute__((address_space(3)))
; __device__ __forceinline__ unsigned cvt_pk_bf16(float lo, float hi) { unsigned r; asm volatile("v_cvt_pk_bf16_f32 %0, %1, %2" : "=v"(r) : "v"(lo), "v"(hi)); return r; }
; #define LDS_WAIT() asm volatile("s_waitcnt lgkmcnt(0)" ::: "memory")
; __device__ __forceinline__ void p0_transpose64(const float* W, int ldw, int K, const float* gain, bf16_t* WT, int nblk, int ncol_src0, int row_off, LAS float* scr, int item, int lane) {
;     ...
;     for (int j = 0; j < 8; ++j) { const int idx = lane + 64 * j, n = idx >> 3, c = idx & 7; const LAS float* sp = scr + (8 * c) * 68 + n;
;         u32x4 o; o.x = cvt_pk_bf16(sp[0 * 68], sp[1 * 68]); o.y = cvt_pk_bf16(sp[2 * 68], sp[3 * 68]); o.z = cvt_pk_bf16(sp[4 * 68], sp[5 * 68]); o.w = cvt_pk_bf16(sp[6 * 68], sp[7 * 68]);
;         *(GAS u32x4*)(WT + (size_t)(row_off + n0 + n) * K + k0 + 8 * c) = o; }
;     LDS_WAIT(); asm volatile("" ::: "memory");
.LBB0_15:
	s_or_b64 exec, exec, s[12:13]
	ds_write_b128 v84, v[2:5] offset:10608
	s_waitcnt lgkmcnt(0)
	v_or_b32_e32 v8, s6, v75
	ds_read_b32 v248, v76
	ds_read_b32 v249, v76 offset:2176
	ds_read_b32 v250, v76 offset:4352
	ds_read_b32 v251, v76 offset:6528
	ds_read_b32 v252, v76 offset:8704
	ds_read_b32 v253, v76 offset:10880
	ds_read_b32 v6, v76 offset:13056
	ds_read_b32 v7, v76 offset:15232
	s_ashr_i32 s11, s10, 31
	v_ashrrev_i32_e32 v9, 31, v8
	s_waitcnt lgkmcnt(0)
	v_cvt_pk_bf16_f32 v2, v248, v249
	v_add_u32_e32 v12, 0x400, v76
	v_lshl_add_u64 v[10:11], s[10:11], 1, v[68:69]
	v_lshlrev_b64 v[8:9], 13, v[8:9]
	s_waitcnt lgkmcnt(0)
	v_cvt_pk_bf16_f32 v3, v250, v251
	v_lshl_add_u64 v[8:9], v[10:11], 0, v[8:9]
	s_waitcnt lgkmcnt(0)
	v_cvt_pk_bf16_f32 v4, v252, v253
	s_waitcnt lgkmcnt(0)
	v_cvt_pk_bf16_f32 v5, v6, v7
	global_store_dwordx4 v[8:9], v[2:5], off
	v_or_b32_e32 v8, s6, v77
	v_ashrrev_i32_e32 v9, 31, v8
	ds_read_b32 v248, v76 offset:32
	ds_read_b32 v249, v76 offset:2208
	ds_read_b32 v250, v76 offset:4384
	ds_read_b32 v251, v76 offset:6560
	ds_read_b32 v252, v76 offset:8736
	ds_read_b32 v253, v76 offset:10912
	ds_read_b32 v6, v76 offset:13088
	ds_read_b32 v7, v76 offset:15264
	s_waitcnt lgkmcnt(0)
	v_cvt_pk_bf16_f32 v2, v248, v249
	v_lshlrev_b64 v[8:9], 13, v[8:9]
	s_waitcnt lgkmcnt(0)
	v_cvt_pk_bf16_f32 v3, v250, v251
	v_lshl_add_u64 v[8:9], v[10:11], 0, v[8:9]
	s_waitcnt lgkmcnt(0)
	v_cvt_pk_bf16_f32 v4, v252, v253
	s_waitcnt lgkmcnt(0)
	v_cvt_pk_bf16_f32 v5, v6, v7
	global_store_dwordx4 v[8:9], v[2:5], off
	v_or_b32_e32 v8, s6, v78
	v_ashrrev_i32_e32 v9, 31, v8
	ds_read_b32 v248, v76 offset:64
	ds_read_b32 v249, v76 offset:2240
	ds_read_b32 v250, v76 offset:4416
	ds_read_b32 v251, v76 offset:6592
	ds_read_b32 v252, v76 offset:8768
	ds_read_b32 v253, v76 offset:10944
	ds_read_b32 v6, v76 offset:13120
	ds_read_b32 v7, v76 offset:15296
	s_waitcnt lgkmcnt(0)
	v_cvt_pk_bf16_f32 v2, v248, v249
	v_lshlrev_b64 v[8:9], 13, v[8:9]
	s_waitcnt lgkmcnt(0)
	v_cvt_pk_bf16_f32 v3, v250, v251
	v_lshl_add_u64 v[8:9], v[10:11], 0, v[8:9]
	s_waitcnt lgkmcnt(0)
	v_cvt_pk_bf16_f32 v4, v252, v253
	s_waitcnt lgkmcnt(0)
	v_cvt_pk_bf16_f32 v5, v6, v7
	global_store_dwordx4 v[8:9], v[2:5], off
	v_or_b32_e32 v8, s6, v79
	v_ashrrev_i32_e32 v9, 31, v8
	ds_read_b32 v248, v76 offset:96
	ds_read_b32 v249, v76 offset:2272
	ds_read_b32 v250, v76 offset:4448
	ds_read_b32 v251, v76 offset:6624
	ds_read_b32 v252, v76 offset:8800
	ds_read_b32 v253, v76 offset:10976
	ds_read_b32 v6, v76 offset:13152
	ds_read_b32 v7, v76 offset:15328
	s_waitcnt lgkmcnt(0)
	v_cvt_pk_bf16_f32 v2, v248, v249
	v_lshlrev_b64 v[8:9], 13, v[8:9]
	s_waitcnt lgkmcnt(0)
	v_cvt_pk_bf16_f32 v3, v250, v251
	v_lshl_add_u64 v[8:9], v[10:11], 0, v[8:9]
	s_waitcnt lgkmcnt(0)
	v_cvt_pk_bf16_f32 v4, v252, v253
	s_waitcnt lgkmcnt(0)
	v_cvt_pk_bf16_f32 v5, v6, v7
	global_store_dwordx4 v[8:9], v[2:5], off
	v_or_b32_e32 v8, s6, v80
	v_ashrrev_i32_e32 v9, 31, v8
	ds_read_b32 v248, v76 offset:128
	ds_read_b32 v249, v76 offset:2304
	ds_read_b32 v250, v76 offset:4480
	ds_read_b32 v251, v76 offset:6656
	ds_read_b32 v252, v76 offset:8832
	ds_read_b32 v253, v76 offset:11008
	ds_read_b32 v6, v76 offset:13184
	ds_read_b32 v7, v76 offset:15360
	s_waitcnt lgkmcnt(0)
	v_cvt_pk_bf16_f32 v2, v248, v249
	v_lshlrev_b64 v[8:9], 13, v[8:9]
	s_waitcnt lgkmcnt(0)
	v_cvt_pk_bf16_f32 v3, v250, v251
	v_lshl_add_u64 v[8:9], v[10:11], 0, v[8:9]
	s_waitcnt lgkmcnt(0)
	v_cvt_pk_bf16_f32 v4, v252, v253
	s_waitcnt lgkmcnt(0)
	v_cvt_pk_bf16_f32 v5, v6, v7
	global_store_dwordx4 v[8:9], v[2:5], off
	v_or_b32_e32 v8, s6, v81
	v_ashrrev_i32_e32 v9, 31, v8
	ds_read_b32 v248, v76 offset:160
	ds_read_b32 v249, v76 offset:2336
	ds_read_b32 v250, v76 offset:4512
	ds_read_b32 v251, v76 offset:6688
	ds_read_b32 v252, v76 offset:8864
	ds_read_b32 v253, v76 offset:11040
	ds_read_b32 v6, v76 offset:13216
	ds_read_b32 v7, v76 offset:15392
	s_waitcnt lgkmcnt(0)
	v_cvt_pk_bf16_f32 v2, v248, v249
	v_lshlrev_b64 v[8:9], 13, v[8:9]
	s_waitcnt lgkmcnt(0)
	v_cvt_pk_bf16_f32 v3, v250, v251
	v_add_u32_e32 v13, 0x600, v76
	v_lshl_add_u64 v[8:9], v[10:11], 0, v[8:9]
	s_waitcnt lgkmcnt(0)
	v_cvt_pk_bf16_f32 v4, v252, v253
	s_waitcnt lgkmcnt(0)
	v_cvt_pk_bf16_f32 v5, v6, v7
	global_store_dwordx4 v[8:9], v[2:5], off
	v_or_b32_e32 v8, s6, v82
	ds_read_b32 v248, v76 offset:192
	ds_read_b32 v249, v76 offset:2368
	ds_read_b32 v250, v76 offset:4544
	ds_read_b32 v251, v76 offset:6720
	ds_read_b32 v252, v76 offset:8896
	ds_read_b32 v253, v76 offset:11072
	ds_read_b32 v6, v76 offset:13248
	ds_read_b32 v7, v76 offset:15424
	s_waitcnt lgkmcnt(0)
	v_cvt_pk_bf16_f32 v2, v248, v249
	v_ashrrev_i32_e32 v9, 31, v8
	s_waitcnt lgkmcnt(0)
	v_cvt_pk_bf16_f32 v3, v250, v251
	v_lshlrev_b64 v[8:9], 13, v[8:9]
	s_waitcnt lgkmcnt(0)
	v_cvt_pk_bf16_f32 v4, v252, v253
	v_add_u32_e32 v14, 0x200, v76
	s_waitcnt lgkmcnt(0)
	v_cvt_pk_bf16_f32 v5, v6, v7
	v_lshl_add_u64 v[8:9], v[10:11], 0, v[8:9]
	ds_read_b32 v248, v76 offset:224
	ds_read_b32 v249, v76 offset:2400
	ds_read_b32 v250, v76 offset:4576
	ds_read_b32 v251, v76 offset:6752
	ds_read_b32 v252, v76 offset:8928
	ds_read_b32 v253, v76 offset:11104
	ds_read_b32 v6, v76 offset:13280
	ds_read_b32 v7, v76 offset:15456
	global_store_dwordx4 v[8:9], v[2:5], off
	v_or_b32_e32 v8, s6, v83
	v_ashrrev_i32_e32 v9, 31, v8
	s_waitcnt lgkmcnt(0)
	v_cvt_pk_bf16_f32 v2, v248, v249
	s_waitcnt lgkmcnt(0)
	v_cvt_pk_bf16_f32 v3, v250, v251
	s_waitcnt lgkmcnt(0)
	v_cvt_pk_bf16_f32 v4, v252, v253
	v_lshlrev_b64 v[8:9], 13, v[8:9]
	s_waitcnt lgkmcnt(0)
	v_cvt_pk_bf16_f32 v5, v6, v7
	v_lshl_add_u64 v[6:7], v[10:11], 0, v[8:9]
	global_store_dwordx4 v[6:7], v[2:5], off
	s_waitcnt lgkmcnt(0)
	s_add_i32 s4, s3, 0x500
	s_cmpk_lt_i32 s3, 0x1300
	s_mov_b32 s3, s4
	s_cbranch_scc0 .LBB0_48

; #define GAS __attribute__((address_space(1)))
; #define LAS __attribute__((address_space(3)))
; __device__ __forceinline__ unsigned cvt_pk_bf16(float lo, float hi) { unsigned r; asm volatile("v_cvt_pk_bf16_f32 %0, %1, %2" : "=v"(r) : "v"(lo), "v"(hi)); return r; }
; #define LDS_WAIT() asm volatile("s_waitcnt lgkmcnt(0)" ::: "memory")
; __device__ __forceinline__ void p0_finish(const P0Item& it, const f32x4 (&w)[16], LAS float* scr, int lane) {
;     ...
;     const unsigned soff = (unsigned)(((lane >> 3) * it.K + 8 * (lane & 7)) * 2);
; #pragma unroll
;     for (int j = 0; j < 8; ++j) { const int n = (lane >> 3) + 8 * j, c = lane & 7; const LAS float* sp = scr + (8 * c) * 68 + n;
;         u32x4 o; o.x = cvt_pk_bf16(sp[0 * 68], sp[1 * 68]); o.y = cvt_pk_bf16(sp[2 * 68], sp[3 * 68]); o.z = cvt_pk_bf16(sp[4 * 68], sp[5 * 68]); o.w = cvt_pk_bf16(sp[6 * 68], sp[7 * 68]);
;         *(GAS u32x4*)((char*)(it.dst + (size_t)(8 * j) * it.K) + soff) = o; }
;     LDS_WAIT(); asm volatile("" ::: "memory");
.LBB0_51:
	s_or_b64 exec, exec, s[20:21]
	s_waitcnt vmcnt(0)
	ds_write_b128 v150, v[66:69] offset:10608
	s_waitcnt lgkmcnt(0)
	s_lshl_b64 s[16:17], s[16:17], 13
	s_add_u32 s16, s72, s16
	ds_read_b32 v248, v149
	ds_read_b32 v249, v149 offset:2176
	ds_read_b32 v250, v149 offset:4352
	ds_read_b32 v251, v149 offset:6528
	ds_read_b32 v252, v149 offset:8704
	ds_read_b32 v253, v149 offset:10880
	ds_read_b32 v70, v149 offset:13056
	ds_read_b32 v71, v149 offset:15232
	s_addc_u32 s17, s73, s17
	s_lshl_b64 s[14:15], s[14:15], 1
	s_waitcnt lgkmcnt(0)
	v_cvt_pk_bf16_f32 v66, v248, v249
	s_add_u32 s14, s16, s14
	s_waitcnt lgkmcnt(0)
	v_cvt_pk_bf16_f32 v67, v250, v251
	s_addc_u32 s15, s17, s15
	s_waitcnt lgkmcnt(0)
	v_cvt_pk_bf16_f32 v68, v252, v253
	s_waitcnt lgkmcnt(0)
	v_cvt_pk_bf16_f32 v69, v70, v71
	v_lshl_add_u64 v[72:73], s[14:15], 0, v[140:141]
	ds_read_b32 v248, v149 offset:32
	ds_read_b32 v249, v149 offset:2208
	ds_read_b32 v250, v149 offset:4384
	ds_read_b32 v251, v149 offset:6560
	ds_read_b32 v252, v149 offset:8736
	ds_read_b32 v253, v149 offset:10912
	ds_read_b32 v70, v149 offset:13088
	ds_read_b32 v71, v149 offset:15264
	global_store_dwordx4 v[72:73], v[66:69], off
	v_add_co_u32_e32 v74, vcc, s34, v72
	s_waitcnt lgkmcnt(0)
	v_cvt_pk_bf16_f32 v66, v248, v249
	s_waitcnt lgkmcnt(0)
	v_cvt_pk_bf16_f32 v67, v250, v251
	s_waitcnt lgkmcnt(0)
	v_cvt_pk_bf16_f32 v68, v252, v253
	s_waitcnt lgkmcnt(0)
	v_cvt_pk_bf16_f32 v69, v70, v71
	v_addc_co_u32_e32 v75, vcc, 0, v73, vcc
	ds_read_b32 v248, v149 offset:64
	ds_read_b32 v249, v149 offset:2240
	ds_read_b32 v250, v149 offset:4416
	ds_read_b32 v251, v149 offset:6592
	ds_read_b32 v252, v149 offset:8768
	ds_read_b32 v253, v149 offset:10944
	ds_read_b32 v70, v149 offset:13120
	ds_read_b32 v71, v149 offset:15296
	global_store_dwordx4 v[74:75], v[66:69], off
	v_add_co_u32_e32 v74, vcc, s35, v72
	s_waitcnt lgkmcnt(0)
	v_cvt_pk_bf16_f32 v66, v248, v249
	s_waitcnt lgkmcnt(0)
	v_cvt_pk_bf16_f32 v67, v250, v251
	s_waitcnt lgkmcnt(0)
	v_cvt_pk_bf16_f32 v68, v252, v253
	s_waitcnt lgkmcnt(0)
	v_cvt_pk_bf16_f32 v69, v70, v71
	v_addc_co_u32_e32 v75, vcc, 0, v73, vcc
	ds_read_b32 v248, v149 offset:96
	ds_read_b32 v249, v149 offset:2272
	ds_read_b32 v250, v149 offset:4448
	ds_read_b32 v251, v149 offset:6624
	ds_read_b32 v252, v149 offset:8800
	ds_read_b32 v253, v149 offset:10976
	ds_read_b32 v70, v149 offset:13152
	ds_read_b32 v71, v149 offset:15328
	global_store_dwordx4 v[74:75], v[66:69], off
	v_add_co_u32_e32 v74, vcc, s3, v72
	s_waitcnt lgkmcnt(0)
	v_cvt_pk_bf16_f32 v66, v248, v249
	s_waitcnt lgkmcnt(0)
	v_cvt_pk_bf16_f32 v67, v250, v251
	s_waitcnt lgkmcnt(0)
	v_cvt_pk_bf16_f32 v68, v252, v253
	s_waitcnt lgkmcnt(0)
	v_cvt_pk_bf16_f32 v69, v70, v71
	v_addc_co_u32_e32 v75, vcc, 0, v73, vcc
	ds_read_b32 v248, v149 offset:128
	ds_read_b32 v249, v149 offset:2304
	ds_read_b32 v250, v149 offset:4480
	ds_read_b32 v251, v149 offset:6656
	ds_read_b32 v252, v149 offset:8832
	ds_read_b32 v253, v149 offset:11008
	ds_read_b32 v70, v149 offset:13184
	ds_read_b32 v71, v149 offset:15360
	global_store_dwordx4 v[74:75], v[66:69], off
	v_add_co_u32_e32 v74, vcc, s36, v72
	s_waitcnt lgkmcnt(0)
	v_cvt_pk_bf16_f32 v66, v248, v249
	s_waitcnt lgkmcnt(0)
	v_cvt_pk_bf16_f32 v67, v250, v251
	s_waitcnt lgkmcnt(0)
	v_cvt_pk_bf16_f32 v68, v252, v253
	s_waitcnt lgkmcnt(0)
	v_cvt_pk_bf16_f32 v69, v70, v71
	v_addc_co_u32_e32 v75, vcc, 0, v73, vcc
	ds_read_b32 v248, v149 offset:160
	ds_read_b32 v249, v149 offset:2336
	ds_read_b32 v250, v149 offset:4512
	ds_read_b32 v251, v149 offset:6688
	ds_read_b32 v252, v149 offset:8864
	ds_read_b32 v253, v149 offset:11040
	ds_read_b32 v70, v149 offset:13216
	ds_read_b32 v71, v149 offset:15392
	global_store_dwordx4 v[74:75], v[66:69], off
	v_add_co_u32_e32 v74, vcc, s37, v72
	s_waitcnt lgkmcnt(0)
	v_cvt_pk_bf16_f32 v66, v248, v249
	s_waitcnt lgkmcnt(0)
	v_cvt_pk_bf16_f32 v67, v250, v251
	s_waitcnt lgkmcnt(0)
	v_cvt_pk_bf16_f32 v68, v252, v253
	s_waitcnt lgkmcnt(0)
	v_cvt_pk_bf16_f32 v69, v70, v71
	v_addc_co_u32_e32 v75, vcc, 0, v73, vcc
	ds_read_b32 v248, v149 offset:192
	ds_read_b32 v249, v149 offset:2368
	ds_read_b32 v250, v149 offset:4544
	ds_read_b32 v251, v149 offset:6720
	ds_read_b32 v252, v149 offset:8896
	ds_read_b32 v253, v149 offset:11072
	ds_read_b32 v70, v149 offset:13248
	ds_read_b32 v71, v149 offset:15424
	global_store_dwordx4 v[74:75], v[66:69], off
	v_add_co_u32_e32 v74, vcc, s22, v72
	s_waitcnt lgkmcnt(0)
	v_cvt_pk_bf16_f32 v66, v248, v249
	s_waitcnt lgkmcnt(0)
	v_cvt_pk_bf16_f32 v67, v250, v251
	s_waitcnt lgkmcnt(0)
	v_cvt_pk_bf16_f32 v68, v252, v253
	s_waitcnt lgkmcnt(0)
	v_cvt_pk_bf16_f32 v69, v70, v71
	v_addc_co_u32_e32 v75, vcc, 0, v73, vcc
	ds_read_b32 v248, v149 offset:224
	ds_read_b32 v249, v149 offset:2400
	ds_read_b32 v250, v149 offset:4576
	ds_read_b32 v251, v149 offset:6752
	ds_read_b32 v252, v149 offset:8928
	ds_read_b32 v253, v149 offset:11104
	ds_read_b32 v70, v149 offset:13280
	ds_read_b32 v71, v149 offset:15456
	global_store_dwordx4 v[74:75], v[66:69], off
	v_add_co_u32_e32 v72, vcc, 0x70000, v72
	s_waitcnt lgkmcnt(0)
	v_cvt_pk_bf16_f32 v66, v248, v249
	s_waitcnt lgkmcnt(0)
	v_cvt_pk_bf16_f32 v67, v250, v251
	v_addc_co_u32_e32 v73, vcc, 0, v73, vcc
	s_waitcnt lgkmcnt(0)
	v_cvt_pk_bf16_f32 v68, v252, v253
	s_waitcnt lgkmcnt(0)
	v_cvt_pk_bf16_f32 v69, v70, v71
	global_store_dwordx4 v[72:73], v[66:69], off
	s_waitcnt lgkmcnt(0)
	s_add_i32 s11, s11, 2
	s_andn2_b64 vcc, exec, s[18:19]
	s_addk_i32 s10, 0xc00
	s_cbranch_vccz .LBB0_62

; #define GAS __attribute__((address_space(1)))
; #define LAS __attribute__((address_space(3)))
; __device__ __forceinline__ unsigned cvt_pk_bf16(float lo, float hi) { unsigned r; asm volatile("v_cvt_pk_bf16_f32 %0, %1, %2" : "=v"(r) : "v"(lo), "v"(hi)); return r; }
; #define LDS_WAIT() asm volatile("s_waitcnt lgkmcnt(0)" ::: "memory")
; __device__ __forceinline__ void p0_finish(const P0Item& it, const f32x4 (&w)[16], LAS float* scr, int lane) {
;     ...
;     const unsigned soff = (unsigned)(((lane >> 3) * it.K + 8 * (lane & 7)) * 2);
; #pragma unroll
;     for (int j = 0; j < 8; ++j) { const int n = (lane >> 3) + 8 * j, c = lane & 7; const LAS float* sp = scr + (8 * c) * 68 + n;
;         u32x4 o; o.x = cvt_pk_bf16(sp[0 * 68], sp[1 * 68]); o.y = cvt_pk_bf16(sp[2 * 68], sp[3 * 68]); o.z = cvt_pk_bf16(sp[4 * 68], sp[5 * 68]); o.w = cvt_pk_bf16(sp[6 * 68], sp[7 * 68]);
;         *(GAS u32x4*)((char*)(it.dst + (size_t)(8 * j) * it.K) + soff) = o; }
;     LDS_WAIT(); asm volatile("" ::: "memory");
.LBB0_56:
	s_or_b64 exec, exec, s[18:19]
	ds_write_b128 v150, v[130:133] offset:10608
	s_waitcnt lgkmcnt(0)
	ds_read_b32 v248, v149
	ds_read_b32 v249, v149 offset:2176
	ds_read_b32 v250, v149 offset:4352
	ds_read_b32 v251, v149 offset:6528
	ds_read_b32 v252, v149 offset:8704
	ds_read_b32 v253, v149 offset:10880
	ds_read_b32 v132, v149 offset:13056
	ds_read_b32 v133, v149 offset:15232
	s_waitcnt lgkmcnt(0)
	v_cvt_pk_bf16_f32 v152, v248, v249
	v_add_u32_e32 v130, 0x400, v149
	s_waitcnt lgkmcnt(0)
	v_cvt_pk_bf16_f32 v153, v250, v251
	s_waitcnt lgkmcnt(0)
	v_cvt_pk_bf16_f32 v154, v252, v253
	s_waitcnt lgkmcnt(0)
	v_cvt_pk_bf16_f32 v155, v132, v133
	ds_read_b32 v248, v149 offset:32
	ds_read_b32 v249, v149 offset:2208
	ds_read_b32 v250, v149 offset:4384
	ds_read_b32 v251, v149 offset:6560
	ds_read_b32 v252, v149 offset:8736
	ds_read_b32 v253, v149 offset:10912
	ds_read_b32 v132, v149 offset:13088
	ds_read_b32 v133, v149 offset:15264
	v_lshl_add_u64 v[156:157], s[12:13], 0, v[140:141]
	global_store_dwordx4 v[156:157], v[152:155], off
	v_add_co_u32_e32 v158, vcc, s34, v156
	s_waitcnt lgkmcnt(0)
	v_cvt_pk_bf16_f32 v152, v248, v249
	s_waitcnt lgkmcnt(0)
	v_cvt_pk_bf16_f32 v153, v250, v251
	s_waitcnt lgkmcnt(0)
	v_cvt_pk_bf16_f32 v154, v252, v253
	s_waitcnt lgkmcnt(0)
	v_cvt_pk_bf16_f32 v155, v132, v133
	ds_read_b32 v248, v149 offset:64
	ds_read_b32 v249, v149 offset:2240
	ds_read_b32 v250, v149 offset:4416
	ds_read_b32 v251, v149 offset:6592
	ds_read_b32 v252, v149 offset:8768
	ds_read_b32 v253, v149 offset:10944
	ds_read_b32 v132, v149 offset:13120
	ds_read_b32 v133, v149 offset:15296
	v_addc_co_u32_e32 v159, vcc, 0, v157, vcc
	global_store_dwordx4 v[158:159], v[152:155], off
	v_add_co_u32_e32 v158, vcc, s35, v156
	s_waitcnt lgkmcnt(0)
	v_cvt_pk_bf16_f32 v152, v248, v249
	s_waitcnt lgkmcnt(0)
	v_cvt_pk_bf16_f32 v153, v250, v251
	s_waitcnt lgkmcnt(0)
	v_cvt_pk_bf16_f32 v154, v252, v253
	s_waitcnt lgkmcnt(0)
	v_cvt_pk_bf16_f32 v155, v132, v133
	ds_read_b32 v248, v149 offset:96
	ds_read_b32 v249, v149 offset:2272
	ds_read_b32 v250, v149 offset:4448
	ds_read_b32 v251, v149 offset:6624
	ds_read_b32 v252, v149 offset:8800
	ds_read_b32 v253, v149 offset:10976
	ds_read_b32 v132, v149 offset:13152
	ds_read_b32 v133, v149 offset:15328
	v_addc_co_u32_e32 v159, vcc, 0, v157, vcc
	global_store_dwordx4 v[158:159], v[152:155], off
	v_add_co_u32_e32 v158, vcc, s3, v156
	s_waitcnt lgkmcnt(0)
	v_cvt_pk_bf16_f32 v152, v248, v249
	s_waitcnt lgkmcnt(0)
	v_cvt_pk_bf16_f32 v153, v250, v251
	s_waitcnt lgkmcnt(0)
	v_cvt_pk_bf16_f32 v154, v252, v253
	s_waitcnt lgkmcnt(0)
	v_cvt_pk_bf16_f32 v155, v132, v133
	ds_read_b32 v248, v149 offset:128
	ds_read_b32 v249, v149 offset:2304
	ds_read_b32 v250, v149 offset:4480
	ds_read_b32 v251, v149 offset:6656
	ds_read_b32 v252, v149 offset:8832
	ds_read_b32 v253, v149 offset:11008
	ds_read_b32 v132, v149 offset:13184
	ds_read_b32 v133, v149 offset:15360
	v_addc_co_u32_e32 v159, vcc, 0, v157, vcc
	global_store_dwordx4 v[158:159], v[152:155], off
	v_add_co_u32_e32 v158, vcc, s36, v156
	s_waitcnt lgkmcnt(0)
	v_cvt_pk_bf16_f32 v152, v248, v249
	s_waitcnt lgkmcnt(0)
	v_cvt_pk_bf16_f32 v153, v250, v251
	s_waitcnt lgkmcnt(0)
	v_cvt_pk_bf16_f32 v154, v252, v253
	s_waitcnt lgkmcnt(0)
	v_cvt_pk_bf16_f32 v155, v132, v133
	ds_read_b32 v248, v149 offset:160
	ds_read_b32 v249, v149 offset:2336
	ds_read_b32 v250, v149 offset:4512
	ds_read_b32 v251, v149 offset:6688
	ds_read_b32 v252, v149 offset:8864
	ds_read_b32 v253, v149 offset:11040
	ds_read_b32 v132, v149 offset:13216
	ds_read_b32 v133, v149 offset:15392
	v_addc_co_u32_e32 v159, vcc, 0, v157, vcc
	global_store_dwordx4 v[158:159], v[152:155], off
	v_add_u32_e32 v131, 0x600, v149
	v_add_co_u32_e32 v158, vcc, s37, v156
	s_waitcnt lgkmcnt(0)
	v_cvt_pk_bf16_f32 v152, v248, v249
	s_waitcnt lgkmcnt(0)
	v_cvt_pk_bf16_f32 v153, v250, v251
	s_waitcnt lgkmcnt(0)
	v_cvt_pk_bf16_f32 v154, v252, v253
	s_waitcnt lgkmcnt(0)
	v_cvt_pk_bf16_f32 v155, v132, v133
	ds_read_b32 v132, v149 offset:192
	ds_read_b32 v133, v149 offset:2368
	v_addc_co_u32_e32 v159, vcc, 0, v157, vcc
	global_store_dwordx4 v[158:159], v[152:155], off
	v_add_co_u32_e32 v160, vcc, s22, v156
	s_waitcnt lgkmcnt(0)
	v_cvt_pk_bf16_f32 v152, v132, v133
	ds_read_b32 v132, v149 offset:4544
	ds_read_b32 v133, v149 offset:6720
	s_waitcnt lgkmcnt(0)
	v_cvt_pk_bf16_f32 v153, v132, v133
	ds_read_b32 v132, v149 offset:8896
	ds_read_b32 v133, v149 offset:11072
	s_waitcnt lgkmcnt(0)
	v_cvt_pk_bf16_f32 v154, v132, v133
	ds_read_b32 v158, v149 offset:13248
	ds_read_b32 v159, v149 offset:15424
	v_add_u32_e32 v132, 0x200, v149
	s_waitcnt lgkmcnt(0)
	v_cvt_pk_bf16_f32 v155, v158, v159
	v_addc_co_u32_e32 v161, vcc, 0, v157, vcc
	ds_read_b32 v248, v149 offset:224
	ds_read_b32 v249, v149 offset:2400
	ds_read_b32 v250, v149 offset:4576
	ds_read_b32 v251, v149 offset:6752
	ds_read_b32 v252, v149 offset:8928
	ds_read_b32 v253, v149 offset:11104
	ds_read_b32 v158, v149 offset:13280
	ds_read_b32 v159, v149 offset:15456
	global_store_dwordx4 v[160:161], v[152:155], off
	v_add_co_u32_e32 v156, vcc, 0x70000, v156
	s_waitcnt lgkmcnt(0)
	v_cvt_pk_bf16_f32 v152, v248, v249
	s_waitcnt lgkmcnt(0)
	v_cvt_pk_bf16_f32 v153, v250, v251
	v_addc_co_u32_e32 v157, vcc, 0, v157, vcc
	s_waitcnt lgkmcnt(0)
	v_cvt_pk_bf16_f32 v154, v252, v253
	s_waitcnt lgkmcnt(0)
	v_cvt_pk_bf16_f32 v155, v158, v159
	global_store_dwordx4 v[156:157], v[152:155], off
	s_waitcnt lgkmcnt(0)
	s_cmp_gt_u32 s11, 5
	s_cselect_b64 s[18:19], -1, 0
	s_and_b64 vcc, exec, s[18:19]
	s_cbranch_vccz .LBB0_59
	s_ashr_i32 s15, s14, 31
	s_and_saveexec_b64 s[20:21], s[4:5]
	s_xor_b64 s[20:21], exec, s[20:21]
	s_cbranch_execnz .LBB0_60

; #define GAS __attribute__((address_space(1)))
; #define LAS __attribute__((address_space(3)))
; __device__ __forceinline__ unsigned cvt_pk_bf16(float lo, float hi) { unsigned r; asm volatile("v_cvt_pk_bf16_f32 %0, %1, %2" : "=v"(r) : "v"(lo), "v"(hi)); return r; }
; #define LDS_WAIT() asm volatile("s_waitcnt lgkmcnt(0)" ::: "memory")
; __device__ __forceinline__ void p0_finish(const P0Item& it, const f32x4 (&w)[16], LAS float* scr, int lane) {
;     ...
;     const unsigned soff = (unsigned)(((lane >> 3) * it.K + 8 * (lane & 7)) * 2);
; #pragma unroll
;     for (int j = 0; j < 8; ++j) { const int n = (lane >> 3) + 8 * j, c = lane & 7; const LAS float* sp = scr + (8 * c) * 68 + n;
;         u32x4 o; o.x = cvt_pk_bf16(sp[0 * 68], sp[1 * 68]); o.y = cvt_pk_bf16(sp[2 * 68], sp[3 * 68]); o.z = cvt_pk_bf16(sp[4 * 68], sp[5 * 68]); o.w = cvt_pk_bf16(sp[6 * 68], sp[7 * 68]);
;         *(GAS u32x4*)((char*)(it.dst + (size_t)(8 * j) * it.K) + soff) = o; }
;     LDS_WAIT(); asm volatile("" ::: "memory");
.LBB0_147:
	s_or_b64 exec, exec, s[22:23]
	s_waitcnt vmcnt(0)
	ds_write_b128 v151, v[66:69] offset:10608
	s_waitcnt lgkmcnt(0)
	s_lshl_b64 s[10:11], s[10:11], 13
	s_add_u32 s10, s33, s10
	ds_read_b32 v248, v154
	ds_read_b32 v249, v154 offset:2176
	ds_read_b32 v250, v154 offset:4352
	ds_read_b32 v251, v154 offset:6528
	ds_read_b32 v252, v154 offset:8704
	ds_read_b32 v253, v154 offset:10880
	ds_read_b32 v70, v154 offset:13056
	ds_read_b32 v71, v154 offset:15232
	s_addc_u32 s11, s60, s11
	s_lshl_b64 s[8:9], s[8:9], 1
	s_waitcnt lgkmcnt(0)
	v_cvt_pk_bf16_f32 v66, v248, v249
	s_add_u32 s8, s10, s8
	s_waitcnt lgkmcnt(0)
	v_cvt_pk_bf16_f32 v67, v250, v251
	s_addc_u32 s9, s11, s9
	s_waitcnt lgkmcnt(0)
	v_cvt_pk_bf16_f32 v68, v252, v253
	s_waitcnt lgkmcnt(0)
	v_cvt_pk_bf16_f32 v69, v70, v71
	v_lshl_add_u64 v[72:73], s[8:9], 0, v[144:145]
	ds_read_b32 v248, v154 offset:32
	ds_read_b32 v249, v154 offset:2208
	ds_read_b32 v250, v154 offset:4384
	ds_read_b32 v251, v154 offset:6560
	ds_read_b32 v252, v154 offset:8736
	ds_read_b32 v253, v154 offset:10912
	ds_read_b32 v70, v154 offset:13088
	ds_read_b32 v71, v154 offset:15264
	global_store_dwordx4 v[72:73], v[66:69], off
	v_add_co_u32_e32 v74, vcc, s42, v72
	s_waitcnt lgkmcnt(0)
	v_cvt_pk_bf16_f32 v66, v248, v249
	s_waitcnt lgkmcnt(0)
	v_cvt_pk_bf16_f32 v67, v250, v251
	s_waitcnt lgkmcnt(0)
	v_cvt_pk_bf16_f32 v68, v252, v253
	s_waitcnt lgkmcnt(0)
	v_cvt_pk_bf16_f32 v69, v70, v71
	v_addc_co_u32_e32 v75, vcc, 0, v73, vcc
	ds_read_b32 v248, v154 offset:64
	ds_read_b32 v249, v154 offset:2240
	ds_read_b32 v250, v154 offset:4416
	ds_read_b32 v251, v154 offset:6592
	ds_read_b32 v252, v154 offset:8768
	ds_read_b32 v253, v154 offset:10944
	ds_read_b32 v70, v154 offset:13120
	ds_read_b32 v71, v154 offset:15296
	global_store_dwordx4 v[74:75], v[66:69], off
	v_add_co_u32_e32 v74, vcc, s43, v72
	s_waitcnt lgkmcnt(0)
	v_cvt_pk_bf16_f32 v66, v248, v249
	s_waitcnt lgkmcnt(0)
	v_cvt_pk_bf16_f32 v67, v250, v251
	s_waitcnt lgkmcnt(0)
	v_cvt_pk_bf16_f32 v68, v252, v253
	s_waitcnt lgkmcnt(0)
	v_cvt_pk_bf16_f32 v69, v70, v71
	v_addc_co_u32_e32 v75, vcc, 0, v73, vcc
	ds_read_b32 v248, v154 offset:96
	ds_read_b32 v249, v154 offset:2272
	ds_read_b32 v250, v154 offset:4448
	ds_read_b32 v251, v154 offset:6624
	ds_read_b32 v252, v154 offset:8800
	ds_read_b32 v253, v154 offset:10976
	ds_read_b32 v70, v154 offset:13152
	ds_read_b32 v71, v154 offset:15328
	global_store_dwordx4 v[74:75], v[66:69], off
	v_add_co_u32_e32 v74, vcc, s44, v72
	s_waitcnt lgkmcnt(0)
	v_cvt_pk_bf16_f32 v66, v248, v249
	s_waitcnt lgkmcnt(0)
	v_cvt_pk_bf16_f32 v67, v250, v251
	s_waitcnt lgkmcnt(0)
	v_cvt_pk_bf16_f32 v68, v252, v253
	s_waitcnt lgkmcnt(0)
	v_cvt_pk_bf16_f32 v69, v70, v71
	v_addc_co_u32_e32 v75, vcc, 0, v73, vcc
	ds_read_b32 v248, v154 offset:128
	ds_read_b32 v249, v154 offset:2304
	ds_read_b32 v250, v154 offset:4480
	ds_read_b32 v251, v154 offset:6656
	ds_read_b32 v252, v154 offset:8832
	ds_read_b32 v253, v154 offset:11008
	ds_read_b32 v70, v154 offset:13184
	ds_read_b32 v71, v154 offset:15360
	global_store_dwordx4 v[74:75], v[66:69], off
	v_add_co_u32_e32 v74, vcc, s27, v72
	s_waitcnt lgkmcnt(0)
	v_cvt_pk_bf16_f32 v66, v248, v249
	s_waitcnt lgkmcnt(0)
	v_cvt_pk_bf16_f32 v67, v250, v251
	s_waitcnt lgkmcnt(0)
	v_cvt_pk_bf16_f32 v68, v252, v253
	s_waitcnt lgkmcnt(0)
	v_cvt_pk_bf16_f32 v69, v70, v71
	v_addc_co_u32_e32 v75, vcc, 0, v73, vcc
	ds_read_b32 v248, v154 offset:160
	ds_read_b32 v249, v154 offset:2336
	ds_read_b32 v250, v154 offset:4512
	ds_read_b32 v251, v154 offset:6688
	ds_read_b32 v252, v154 offset:8864
	ds_read_b32 v253, v154 offset:11040
	ds_read_b32 v70, v154 offset:13216
	ds_read_b32 v71, v154 offset:15392
	global_store_dwordx4 v[74:75], v[66:69], off
	v_add_co_u32_e32 v74, vcc, s45, v72
	s_waitcnt lgkmcnt(0)
	v_cvt_pk_bf16_f32 v66, v248, v249
	s_waitcnt lgkmcnt(0)
	v_cvt_pk_bf16_f32 v67, v250, v251
	s_waitcnt lgkmcnt(0)
	v_cvt_pk_bf16_f32 v68, v252, v253
	s_waitcnt lgkmcnt(0)
	v_cvt_pk_bf16_f32 v69, v70, v71
	v_addc_co_u32_e32 v75, vcc, 0, v73, vcc
	ds_read_b32 v248, v154 offset:192
	ds_read_b32 v249, v154 offset:2368
	ds_read_b32 v250, v154 offset:4544
	ds_read_b32 v251, v154 offset:6720
	ds_read_b32 v252, v154 offset:8896
	ds_read_b32 v253, v154 offset:11072
	ds_read_b32 v70, v154 offset:13248
	ds_read_b32 v71, v154 offset:15424
	global_store_dwordx4 v[74:75], v[66:69], off
	v_add_co_u32_e32 v74, vcc, s46, v72
	s_waitcnt lgkmcnt(0)
	v_cvt_pk_bf16_f32 v66, v248, v249
	s_waitcnt lgkmcnt(0)
	v_cvt_pk_bf16_f32 v67, v250, v251
	s_waitcnt lgkmcnt(0)
	v_cvt_pk_bf16_f32 v68, v252, v253
	s_waitcnt lgkmcnt(0)
	v_cvt_pk_bf16_f32 v69, v70, v71
	v_addc_co_u32_e32 v75, vcc, 0, v73, vcc
	ds_read_b32 v248, v154 offset:224
	ds_read_b32 v249, v154 offset:2400
	ds_read_b32 v250, v154 offset:4576
	ds_read_b32 v251, v154 offset:6752
	ds_read_b32 v252, v154 offset:8928
	ds_read_b32 v253, v154 offset:11104
	ds_read_b32 v70, v154 offset:13280
	ds_read_b32 v71, v154 offset:15456
	global_store_dwordx4 v[74:75], v[66:69], off
	v_add_co_u32_e32 v72, vcc, 0x70000, v72
	s_waitcnt lgkmcnt(0)
	v_cvt_pk_bf16_f32 v66, v248, v249
	s_waitcnt lgkmcnt(0)
	v_cvt_pk_bf16_f32 v67, v250, v251
	v_addc_co_u32_e32 v73, vcc, 0, v73, vcc
	s_waitcnt lgkmcnt(0)
	v_cvt_pk_bf16_f32 v68, v252, v253
	s_waitcnt lgkmcnt(0)
	v_cvt_pk_bf16_f32 v69, v70, v71
	global_store_dwordx4 v[72:73], v[66:69], off
	s_waitcnt lgkmcnt(0)
	s_add_i32 s26, s26, 2
	s_andn2_b64 vcc, exec, s[12:13]
	s_addk_i32 s41, 0x1000
	s_cbranch_vccz .LBB0_158

; #define GAS __attribute__((address_space(1)))
; #define LAS __attribute__((address_space(3)))
; __device__ __forceinline__ unsigned cvt_pk_bf16(float lo, float hi) { unsigned r; asm volatile("v_cvt_pk_bf16_f32 %0, %1, %2" : "=v"(r) : "v"(lo), "v"(hi)); return r; }
; #define LDS_WAIT() asm volatile("s_waitcnt lgkmcnt(0)" ::: "memory")
; __device__ __forceinline__ void p0_finish(const P0Item& it, const f32x4 (&w)[16], LAS float* scr, int lane) {
;     ...
;     const unsigned soff = (unsigned)(((lane >> 3) * it.K + 8 * (lane & 7)) * 2);
; #pragma unroll
;     for (int j = 0; j < 8; ++j) { const int n = (lane >> 3) + 8 * j, c = lane & 7; const LAS float* sp = scr + (8 * c) * 68 + n;
;         u32x4 o; o.x = cvt_pk_bf16(sp[0 * 68], sp[1 * 68]); o.y = cvt_pk_bf16(sp[2 * 68], sp[3 * 68]); o.z = cvt_pk_bf16(sp[4 * 68], sp[5 * 68]); o.w = cvt_pk_bf16(sp[6 * 68], sp[7 * 68]);
;         *(GAS u32x4*)((char*)(it.dst + (size_t)(8 * j) * it.K) + soff) = o; }
;     LDS_WAIT(); asm volatile("" ::: "memory");
.LBB0_152:
	s_or_b64 exec, exec, s[12:13]
	ds_write_b128 v151, v[130:133] offset:10608
	s_waitcnt lgkmcnt(0)
	ds_read_b32 v248, v154
	ds_read_b32 v249, v154 offset:2176
	ds_read_b32 v250, v154 offset:4352
	ds_read_b32 v251, v154 offset:6528
	ds_read_b32 v252, v154 offset:8704
	ds_read_b32 v253, v154 offset:10880
	ds_read_b32 v132, v154 offset:13056
	ds_read_b32 v133, v154 offset:15232
	s_waitcnt lgkmcnt(0)
	v_cvt_pk_bf16_f32 v156, v248, v249
	v_add_u32_e32 v130, 0x400, v154
	s_waitcnt lgkmcnt(0)
	v_cvt_pk_bf16_f32 v157, v250, v251
	s_waitcnt lgkmcnt(0)
	v_cvt_pk_bf16_f32 v158, v252, v253
	s_waitcnt lgkmcnt(0)
	v_cvt_pk_bf16_f32 v159, v132, v133
	ds_read_b32 v248, v154 offset:32
	ds_read_b32 v249, v154 offset:2208
	ds_read_b32 v250, v154 offset:4384
	ds_read_b32 v251, v154 offset:6560
	ds_read_b32 v252, v154 offset:8736
	ds_read_b32 v253, v154 offset:10912
	ds_read_b32 v132, v154 offset:13088
	ds_read_b32 v133, v154 offset:15264
	v_lshl_add_u64 v[160:161], s[0:1], 0, v[144:145]
	global_store_dwordx4 v[160:161], v[156:159], off
	v_add_co_u32_e32 v162, vcc, s42, v160
	s_waitcnt lgkmcnt(0)
	v_cvt_pk_bf16_f32 v156, v248, v249
	s_waitcnt lgkmcnt(0)
	v_cvt_pk_bf16_f32 v157, v250, v251
	s_waitcnt lgkmcnt(0)
	v_cvt_pk_bf16_f32 v158, v252, v253
	s_waitcnt lgkmcnt(0)
	v_cvt_pk_bf16_f32 v159, v132, v133
	ds_read_b32 v248, v154 offset:64
	ds_read_b32 v249, v154 offset:2240
	ds_read_b32 v250, v154 offset:4416
	ds_read_b32 v251, v154 offset:6592
	ds_read_b32 v252, v154 offset:8768
	ds_read_b32 v253, v154 offset:10944
	ds_read_b32 v132, v154 offset:13120
	ds_read_b32 v133, v154 offset:15296
	v_addc_co_u32_e32 v163, vcc, 0, v161, vcc
	global_store_dwordx4 v[162:163], v[156:159], off
	v_add_co_u32_e32 v162, vcc, s43, v160
	s_waitcnt lgkmcnt(0)
	v_cvt_pk_bf16_f32 v156, v248, v249
	s_waitcnt lgkmcnt(0)
	v_cvt_pk_bf16_f32 v157, v250, v251
	s_waitcnt lgkmcnt(0)
	v_cvt_pk_bf16_f32 v158, v252, v253
	s_waitcnt lgkmcnt(0)
	v_cvt_pk_bf16_f32 v159, v132, v133
	ds_read_b32 v248, v154 offset:96
	ds_read_b32 v249, v154 offset:2272
	ds_read_b32 v250, v154 offset:4448
	ds_read_b32 v251, v154 offset:6624
	ds_read_b32 v252, v154 offset:8800
	ds_read_b32 v253, v154 offset:10976
	ds_read_b32 v132, v154 offset:13152
	ds_read_b32 v133, v154 offset:15328
	v_addc_co_u32_e32 v163, vcc, 0, v161, vcc
	global_store_dwordx4 v[162:163], v[156:159], off
	v_add_co_u32_e32 v162, vcc, s44, v160
	s_waitcnt lgkmcnt(0)
	v_cvt_pk_bf16_f32 v156, v248, v249
	s_waitcnt lgkmcnt(0)
	v_cvt_pk_bf16_f32 v157, v250, v251
	s_waitcnt lgkmcnt(0)
	v_cvt_pk_bf16_f32 v158, v252, v253
	s_waitcnt lgkmcnt(0)
	v_cvt_pk_bf16_f32 v159, v132, v133
	ds_read_b32 v248, v154 offset:128
	ds_read_b32 v249, v154 offset:2304
	ds_read_b32 v250, v154 offset:4480
	ds_read_b32 v251, v154 offset:6656
	ds_read_b32 v252, v154 offset:8832
	ds_read_b32 v253, v154 offset:11008
	ds_read_b32 v132, v154 offset:13184
	ds_read_b32 v133, v154 offset:15360
	v_addc_co_u32_e32 v163, vcc, 0, v161, vcc
	global_store_dwordx4 v[162:163], v[156:159], off
	v_add_co_u32_e32 v162, vcc, s27, v160
	s_waitcnt lgkmcnt(0)
	v_cvt_pk_bf16_f32 v156, v248, v249
	s_waitcnt lgkmcnt(0)
	v_cvt_pk_bf16_f32 v157, v250, v251
	s_waitcnt lgkmcnt(0)
	v_cvt_pk_bf16_f32 v158, v252, v253
	s_waitcnt lgkmcnt(0)
	v_cvt_pk_bf16_f32 v159, v132, v133
	ds_read_b32 v248, v154 offset:160
	ds_read_b32 v249, v154 offset:2336
	ds_read_b32 v250, v154 offset:4512
	ds_read_b32 v251, v154 offset:6688
	ds_read_b32 v252, v154 offset:8864
	ds_read_b32 v253, v154 offset:11040
	ds_read_b32 v132, v154 offset:13216
	ds_read_b32 v133, v154 offset:15392
	v_addc_co_u32_e32 v163, vcc, 0, v161, vcc
	global_store_dwordx4 v[162:163], v[156:159], off
	v_add_u32_e32 v131, 0x600, v154
	v_add_co_u32_e32 v162, vcc, s45, v160
	s_waitcnt lgkmcnt(0)
	v_cvt_pk_bf16_f32 v156, v248, v249
	s_waitcnt lgkmcnt(0)
	v_cvt_pk_bf16_f32 v157, v250, v251
	s_waitcnt lgkmcnt(0)
	v_cvt_pk_bf16_f32 v158, v252, v253
	s_waitcnt lgkmcnt(0)
	v_cvt_pk_bf16_f32 v159, v132, v133
	ds_read_b32 v132, v154 offset:192
	ds_read_b32 v133, v154 offset:2368
	v_addc_co_u32_e32 v163, vcc, 0, v161, vcc
	global_store_dwordx4 v[162:163], v[156:159], off
	v_add_co_u32_e32 v164, vcc, s46, v160
	s_waitcnt lgkmcnt(0)
	v_cvt_pk_bf16_f32 v156, v132, v133
	ds_read_b32 v132, v154 offset:4544
	ds_read_b32 v133, v154 offset:6720
	s_waitcnt lgkmcnt(0)
	v_cvt_pk_bf16_f32 v157, v132, v133
	ds_read_b32 v132, v154 offset:8896
	ds_read_b32 v133, v154 offset:11072
	s_waitcnt lgkmcnt(0)
	v_cvt_pk_bf16_f32 v158, v132, v133
	ds_read_b32 v162, v154 offset:13248
	ds_read_b32 v163, v154 offset:15424
	v_add_u32_e32 v132, 0x200, v154
	s_waitcnt lgkmcnt(0)
	v_cvt_pk_bf16_f32 v159, v162, v163
	v_addc_co_u32_e32 v165, vcc, 0, v161, vcc
	ds_read_b32 v248, v154 offset:224
	ds_read_b32 v249, v154 offset:2400
	ds_read_b32 v250, v154 offset:4576
	ds_read_b32 v251, v154 offset:6752
	ds_read_b32 v252, v154 offset:8928
	ds_read_b32 v253, v154 offset:11104
	ds_read_b32 v162, v154 offset:13280
	ds_read_b32 v163, v154 offset:15456
	global_store_dwordx4 v[164:165], v[156:159], off
	v_add_co_u32_e32 v160, vcc, 0x70000, v160
	s_waitcnt lgkmcnt(0)
	v_cvt_pk_bf16_f32 v156, v248, v249
	s_waitcnt lgkmcnt(0)
	v_cvt_pk_bf16_f32 v157, v250, v251
	v_addc_co_u32_e32 v161, vcc, 0, v161, vcc
	s_waitcnt lgkmcnt(0)
	v_cvt_pk_bf16_f32 v158, v252, v253
	s_waitcnt lgkmcnt(0)
	v_cvt_pk_bf16_f32 v159, v162, v163
	global_store_dwordx4 v[160:161], v[156:159], off
	s_waitcnt lgkmcnt(0)
	s_cmp_gt_u32 s26, 5
	s_cselect_b64 s[12:13], -1, 0
	s_and_b64 vcc, exec, s[12:13]
	s_cbranch_vccz .LBB0_155
	s_and_saveexec_b64 s[22:23], s[4:5]
	s_xor_b64 s[22:23], exec, s[22:23]
	s_cbranch_execnz .LBB0_156

; #define GAS __attribute__((address_space(1)))
; #define LAS __attribute__((address_space(3)))
; __device__ __forceinline__ unsigned cvt_pk_bf16(float lo, float hi) { unsigned r; asm volatile("v_cvt_pk_bf16_f32 %0, %1, %2" : "=v"(r) : "v"(lo), "v"(hi)); return r; }
; #define LDS_WAIT() asm volatile("s_waitcnt lgkmcnt(0)" ::: "memory")
; __device__ __forceinline__ void p0_finish(const P0Item& it, const f32x4 (&w)[16], LAS float* scr, int lane) {
;     ...
;     else {
; #pragma unroll
;         for (int i = 0; i < 16; ++i) *(LAS f32x4*)(scr + (kr + 4 * i) * 68 + c4) = w[i]; }
;     LDS_WAIT(); asm volatile("" ::: "memory");
;     const unsigned soff = (unsigned)(((lane >> 3) * it.K + 8 * (lane & 7)) * 2);
; #pragma unroll
;     for (int j = 0; j < 8; ++j) { const int n = (lane >> 3) + 8 * j, c = lane & 7; const LAS float* sp = scr + (8 * c) * 68 + n;
;         u32x4 o; o.x = cvt_pk_bf16(sp[0 * 68], sp[1 * 68]); o.y = cvt_pk_bf16(sp[2 * 68], sp[3 * 68]); o.z = cvt_pk_bf16(sp[4 * 68], sp[5 * 68]); o.w = cvt_pk_bf16(sp[6 * 68], sp[7 * 68]);
;         *(GAS u32x4*)((char*)(it.dst + (size_t)(8 * j) * it.K) + soff) = o; }
;     LDS_WAIT(); asm volatile("" ::: "memory");
.LBB0_182:
	ds_write_b128 v151, v[66:69]
	ds_write_b128 v151, v[70:73] offset:8704
	ds_write_b128 v151, v[74:77] offset:272
	ds_write_b128 v151, v[78:81] offset:8976
	ds_write_b128 v151, v[82:85] offset:544
	ds_write_b128 v151, v[86:89] offset:9248
	ds_write_b128 v151, v[90:93] offset:816
	ds_write_b128 v151, v[94:97] offset:9520
	ds_write_b128 v151, v[98:101] offset:1088
	ds_write_b128 v151, v[102:105] offset:9792
	ds_write_b128 v151, v[106:109] offset:1360
	ds_write_b128 v151, v[110:113] offset:10064
	ds_write_b128 v151, v[114:117] offset:1632
	ds_write_b128 v151, v[118:121] offset:10336
	ds_write_b128 v151, v[122:125] offset:1904
	ds_write_b128 v151, v[126:129] offset:10608
	s_waitcnt lgkmcnt(0)
	ds_read_b32 v248, v154
	ds_read_b32 v249, v154 offset:2176
	ds_read_b32 v250, v154 offset:4352
	ds_read_b32 v251, v154 offset:6528
	ds_read_b32 v252, v154 offset:8704
	ds_read_b32 v253, v154 offset:10880
	ds_read_b32 v70, v154 offset:13056
	ds_read_b32 v71, v154 offset:15232
	s_waitcnt lgkmcnt(0)
	v_cvt_pk_bf16_f32 v66, v248, v249
	v_mul_lo_u32 v72, s8, v152
	s_waitcnt lgkmcnt(0)
	v_cvt_pk_bf16_f32 v67, v250, v251
	v_or_b32_e32 v72, v72, v153
	s_waitcnt lgkmcnt(0)
	v_cvt_pk_bf16_f32 v68, v252, v253
	s_waitcnt lgkmcnt(0)
	v_cvt_pk_bf16_f32 v69, v70, v71
	v_lshlrev_b32_e32 v72, 1, v72
	s_mov_b32 s9, s1
	ds_read_b32 v248, v154 offset:32
	ds_read_b32 v249, v154 offset:2208
	ds_read_b32 v250, v154 offset:4384
	ds_read_b32 v251, v154 offset:6560
	ds_read_b32 v252, v154 offset:8736
	ds_read_b32 v253, v154 offset:10912
	ds_read_b32 v70, v154 offset:13088
	ds_read_b32 v71, v154 offset:15264
	global_store_dwordx4 v72, v[66:69], s[6:7]
	s_lshl_b64 s[8:9], s[8:9], 4
	s_add_u32 s6, s6, s8
	s_waitcnt lgkmcnt(0)
	v_cvt_pk_bf16_f32 v66, v248, v249
	s_waitcnt lgkmcnt(0)
	v_cvt_pk_bf16_f32 v67, v250, v251
	s_waitcnt lgkmcnt(0)
	v_cvt_pk_bf16_f32 v68, v252, v253
	s_waitcnt lgkmcnt(0)
	v_cvt_pk_bf16_f32 v69, v70, v71
	s_addc_u32 s7, s7, s9
	ds_read_b32 v248, v154 offset:64
	ds_read_b32 v249, v154 offset:2240
	ds_read_b32 v250, v154 offset:4416
	ds_read_b32 v251, v154 offset:6592
	ds_read_b32 v252, v154 offset:8768
	ds_read_b32 v253, v154 offset:10944
	ds_read_b32 v70, v154 offset:13120
	ds_read_b32 v71, v154 offset:15296
	global_store_dwordx4 v72, v[66:69], s[6:7]
	s_add_u32 s6, s6, s8
	s_addc_u32 s7, s7, s9
	s_waitcnt lgkmcnt(0)
	v_cvt_pk_bf16_f32 v66, v248, v249
	s_waitcnt lgkmcnt(0)
	v_cvt_pk_bf16_f32 v67, v250, v251
	s_waitcnt lgkmcnt(0)
	v_cvt_pk_bf16_f32 v68, v252, v253
	s_waitcnt lgkmcnt(0)
	v_cvt_pk_bf16_f32 v69, v70, v71
	ds_read_b32 v248, v154 offset:96
	ds_read_b32 v249, v154 offset:2272
	ds_read_b32 v250, v154 offset:4448
	ds_read_b32 v251, v154 offset:6624
	ds_read_b32 v252, v154 offset:8800
	ds_read_b32 v253, v154 offset:10976
	ds_read_b32 v70, v154 offset:13152
	ds_read_b32 v71, v154 offset:15328
	global_store_dwordx4 v72, v[66:69], s[6:7]
	s_add_u32 s6, s6, s8
	s_addc_u32 s7, s7, s9
	s_waitcnt lgkmcnt(0)
	v_cvt_pk_bf16_f32 v66, v248, v249
	s_waitcnt lgkmcnt(0)
	v_cvt_pk_bf16_f32 v67, v250, v251
	s_waitcnt lgkmcnt(0)
	v_cvt_pk_bf16_f32 v68, v252, v253
	s_waitcnt lgkmcnt(0)
	v_cvt_pk_bf16_f32 v69, v70, v71
	ds_read_b32 v248, v154 offset:128
	ds_read_b32 v249, v154 offset:2304
	ds_read_b32 v250, v154 offset:4480
	ds_read_b32 v251, v154 offset:6656
	ds_read_b32 v252, v154 offset:8832
	ds_read_b32 v253, v154 offset:11008
	ds_read_b32 v70, v154 offset:13184
	ds_read_b32 v71, v154 offset:15360
	global_store_dwordx4 v72, v[66:69], s[6:7]
	s_add_u32 s6, s6, s8
	s_addc_u32 s7, s7, s9
	s_waitcnt lgkmcnt(0)
	v_cvt_pk_bf16_f32 v66, v248, v249
	s_waitcnt lgkmcnt(0)
	v_cvt_pk_bf16_f32 v67, v250, v251
	s_waitcnt lgkmcnt(0)
	v_cvt_pk_bf16_f32 v68, v252, v253
	s_waitcnt lgkmcnt(0)
	v_cvt_pk_bf16_f32 v69, v70, v71
	ds_read_b32 v248, v154 offset:160
	ds_read_b32 v249, v154 offset:2336
	ds_read_b32 v250, v154 offset:4512
	ds_read_b32 v251, v154 offset:6688
	ds_read_b32 v252, v154 offset:8864
	ds_read_b32 v253, v154 offset:11040
	ds_read_b32 v70, v154 offset:13216
	ds_read_b32 v71, v154 offset:15392
	global_store_dwordx4 v72, v[66:69], s[6:7]
	s_add_u32 s6, s6, s8
	s_addc_u32 s7, s7, s9
	s_waitcnt lgkmcnt(0)
	v_cvt_pk_bf16_f32 v66, v248, v249
	s_waitcnt lgkmcnt(0)
	v_cvt_pk_bf16_f32 v67, v250, v251
	s_waitcnt lgkmcnt(0)
	v_cvt_pk_bf16_f32 v68, v252, v253
	s_waitcnt lgkmcnt(0)
	v_cvt_pk_bf16_f32 v69, v70, v71
	ds_read_b32 v248, v154 offset:192
	ds_read_b32 v249, v154 offset:2368
	ds_read_b32 v250, v154 offset:4544
	ds_read_b32 v251, v154 offset:6720
	ds_read_b32 v252, v154 offset:8896
	ds_read_b32 v253, v154 offset:11072
	ds_read_b32 v70, v154 offset:13248
	ds_read_b32 v71, v154 offset:15424
	global_store_dwordx4 v72, v[66:69], s[6:7]
	s_add_u32 s6, s6, s8
	s_addc_u32 s7, s7, s9
	s_waitcnt lgkmcnt(0)
	v_cvt_pk_bf16_f32 v66, v248, v249
	s_waitcnt lgkmcnt(0)
	v_cvt_pk_bf16_f32 v67, v250, v251
	s_waitcnt lgkmcnt(0)
	v_cvt_pk_bf16_f32 v68, v252, v253
	s_waitcnt lgkmcnt(0)
	v_cvt_pk_bf16_f32 v69, v70, v71
	ds_read_b32 v248, v154 offset:224
	ds_read_b32 v249, v154 offset:2400
	ds_read_b32 v250, v154 offset:4576
	ds_read_b32 v251, v154 offset:6752
	ds_read_b32 v252, v154 offset:8928
	ds_read_b32 v253, v154 offset:11104
	ds_read_b32 v70, v154 offset:13280
	ds_read_b32 v71, v154 offset:15456
	global_store_dwordx4 v72, v[66:69], s[6:7]
	s_add_u32 s6, s6, s8
	s_addc_u32 s7, s7, s9
	s_waitcnt lgkmcnt(0)
	v_cvt_pk_bf16_f32 v66, v248, v249
	s_waitcnt lgkmcnt(0)
	v_cvt_pk_bf16_f32 v67, v250, v251
	s_waitcnt lgkmcnt(0)
	v_cvt_pk_bf16_f32 v68, v252, v253
	s_waitcnt lgkmcnt(0)
	v_cvt_pk_bf16_f32 v69, v70, v71
	global_store_dwordx4 v72, v[66:69], s[6:7]
	s_waitcnt lgkmcnt(0)
	s_add_i32 s26, s26, 2
	s_add_i32 s22, s22, 16
	s_andn2_b64 vcc, exec, s[10:11]
	s_addk_i32 s23, 0x400
	s_cbranch_vccz .LBB0_216

; #define GAS __attribute__((address_space(1)))
; #define LAS __attribute__((address_space(3)))
; __device__ __forceinline__ unsigned cvt_pk_bf16(float lo, float hi) { unsigned r; asm volatile("v_cvt_pk_bf16_f32 %0, %1, %2" : "=v"(r) : "v"(lo), "v"(hi)); return r; }
; #define LDS_WAIT() asm volatile("s_waitcnt lgkmcnt(0)" ::: "memory")
; __device__ __forceinline__ void p0_load(const P0Item& it, f32x4 (&w)[16], int lane) {
;     const unsigned voff = (unsigned)(((lane >> 4) * it.ldw + (lane & 15) * 4) * 4);
; #pragma unroll
;     for (int i = 0; i < 16; ++i) w[i] = __builtin_nontemporal_load((const f32x4*)((const char*)(it.src + (size_t)(4 * i) * it.ldw) + voff));
; }
; __device__ __forceinline__ void p0_finish(const P0Item& it, const f32x4 (&w)[16], LAS float* scr, int lane) {
;     const int c4 = (lane & 15) * 4, kr = lane >> 4;
;     if (it.gain) { const unsigned goff = (unsigned)(kr * 4);
; #pragma unroll
;         for (int i = 0; i < 16; ++i) { const float g = *(const float*)((const char*)(it.gain + 4 * i) + goff); *(LAS f32x4*)(scr + (kr + 4 * i) * 68 + c4) = w[i] * g; } }
;     else {
; #pragma unroll
;         for (int i = 0; i < 16; ++i) *(LAS f32x4*)(scr + (kr + 4 * i) * 68 + c4) = w[i]; }
;     LDS_WAIT(); asm volatile("" ::: "memory");
;     const unsigned soff = (unsigned)(((lane >> 3) * it.K + 8 * (lane & 7)) * 2);
; #pragma unroll
;     for (int j = 0; j < 8; ++j) { const int n = (lane >> 3) + 8 * j, c = lane & 7; const LAS float* sp = scr + (8 * c) * 68 + n;
;         u32x4 o; o.x = cvt_pk_bf16(sp[0 * 68], sp[1 * 68]); o.y = cvt_pk_bf16(sp[2 * 68], sp[3 * 68]); o.z = cvt_pk_bf16(sp[4 * 68], sp[5 * 68]); o.w = cvt_pk_bf16(sp[6 * 68], sp[7 * 68]);
;         *(GAS u32x4*)((char*)(it.dst + (size_t)(8 * j) * it.K) + soff) = o; }
;     LDS_WAIT(); asm volatile("" ::: "memory");
.LBB0_199:
	v_lshl_add_u64 v[122:123], v[66:67], 0, v[144:145]
	v_add_co_u32_e32 v70, vcc, 0x10000, v122
	v_add_u32_e32 v137, 0x400, v154
	s_nop 0
	v_addc_co_u32_e32 v71, vcc, 0, v123, vcc
	v_add_co_u32_e32 v74, vcc, 0x20000, v122
	flat_load_dwordx4 v[66:69], v[122:123] nt
	s_nop 0
	flat_load_dwordx4 v[70:73], v[70:71] nt
	v_addc_co_u32_e32 v75, vcc, 0, v123, vcc
	v_add_co_u32_e32 v78, vcc, 0x30000, v122
	v_mul_lo_u32 v155, s0, v152
	s_nop 0
	v_addc_co_u32_e32 v79, vcc, 0, v123, vcc
	v_add_co_u32_e32 v82, vcc, 0x40000, v122
	flat_load_dwordx4 v[74:77], v[74:75] nt
	s_nop 0
	flat_load_dwordx4 v[78:81], v[78:79] nt
	v_addc_co_u32_e32 v83, vcc, 0, v123, vcc
	v_add_co_u32_e32 v86, vcc, 0x50000, v122
	v_add_lshl_u32 v155, v155, v153, 1
	s_nop 0
	v_addc_co_u32_e32 v87, vcc, 0, v123, vcc
	v_add_co_u32_e32 v90, vcc, 0x60000, v122
	flat_load_dwordx4 v[82:85], v[82:83] nt
	s_nop 0
	flat_load_dwordx4 v[86:89], v[86:87] nt
	v_addc_co_u32_e32 v91, vcc, 0, v123, vcc
	v_add_co_u32_e32 v94, vcc, 0x70000, v122
	s_lshl_b64 s[10:11], s[0:1], 4
	s_nop 0
	v_addc_co_u32_e32 v95, vcc, 0, v123, vcc
	v_add_co_u32_e32 v98, vcc, 0x80000, v122
	flat_load_dwordx4 v[90:93], v[90:91] nt
	s_nop 0
	flat_load_dwordx4 v[94:97], v[94:95] nt
	v_addc_co_u32_e32 v99, vcc, 0, v123, vcc
	v_add_co_u32_e32 v102, vcc, 0x90000, v122
	s_add_u32 s12, s4, s10
	s_nop 0
	v_addc_co_u32_e32 v103, vcc, 0, v123, vcc
	v_add_co_u32_e32 v106, vcc, 0xa0000, v122
	flat_load_dwordx4 v[98:101], v[98:99] nt
	s_nop 0
	flat_load_dwordx4 v[102:105], v[102:103] nt
	v_addc_co_u32_e32 v107, vcc, 0, v123, vcc
	v_add_co_u32_e32 v110, vcc, 0xb0000, v122
	s_addc_u32 s13, s5, s11
	s_nop 0
	v_addc_co_u32_e32 v111, vcc, 0, v123, vcc
	v_add_co_u32_e32 v114, vcc, 0xc0000, v122
	flat_load_dwordx4 v[106:109], v[106:107] nt
	s_nop 0
	flat_load_dwordx4 v[110:113], v[110:111] nt
	v_addc_co_u32_e32 v115, vcc, 0, v123, vcc
	v_add_co_u32_e32 v118, vcc, 0xd0000, v122
	s_nop 1
	v_addc_co_u32_e32 v119, vcc, 0, v123, vcc
	v_add_co_u32_e32 v124, vcc, 0xe0000, v122
	flat_load_dwordx4 v[114:117], v[114:115] nt
	s_nop 0
	flat_load_dwordx4 v[118:121], v[118:119] nt
	v_addc_co_u32_e32 v125, vcc, 0, v123, vcc
	v_add_co_u32_e32 v126, vcc, 0xf0000, v122
	s_nop 1
	v_addc_co_u32_e32 v127, vcc, 0, v123, vcc
	flat_load_dwordx4 v[122:125], v[124:125] nt
	s_nop 0
	flat_load_dwordx4 v[126:129], v[126:127] nt
	s_waitcnt vmcnt(0) lgkmcnt(0)
	ds_write_b128 v151, v[2:5]
	ds_write_b128 v151, v[6:9] offset:8704
	ds_write_b128 v151, v[10:13] offset:272
	ds_write_b128 v151, v[14:17] offset:8976
	ds_write_b128 v151, v[18:21] offset:544
	ds_write_b128 v151, v[22:25] offset:9248
	ds_write_b128 v151, v[26:29] offset:816
	ds_write_b128 v151, v[30:33] offset:9520
	ds_write_b128 v151, v[34:37] offset:1088
	ds_write_b128 v151, v[38:41] offset:9792
	ds_write_b128 v151, v[42:45] offset:1360
	ds_write_b128 v151, v[46:49] offset:10064
	ds_write_b128 v151, v[50:53] offset:1632
	ds_write_b128 v151, v[54:57] offset:10336
	ds_write_b128 v151, v[58:61] offset:1904
	ds_write_b128 v151, v[62:65] offset:10608
	s_waitcnt lgkmcnt(0)
	ds_read_b32 v248, v154
	ds_read_b32 v249, v154 offset:2176
	ds_read_b32 v250, v154 offset:4352
	ds_read_b32 v251, v154 offset:6528
	ds_read_b32 v252, v154 offset:8704
	ds_read_b32 v253, v154 offset:10880
	ds_read_b32 v156, v154 offset:13056
	ds_read_b32 v157, v154 offset:15232
	s_waitcnt lgkmcnt(0)
	v_cvt_pk_bf16_f32 v146, v248, v249
	s_waitcnt lgkmcnt(0)
	v_cvt_pk_bf16_f32 v147, v250, v251
	s_waitcnt lgkmcnt(0)
	v_cvt_pk_bf16_f32 v148, v252, v253
	s_waitcnt lgkmcnt(0)
	v_cvt_pk_bf16_f32 v149, v156, v157
	ds_read_b32 v248, v154 offset:32
	ds_read_b32 v249, v154 offset:2208
	ds_read_b32 v250, v154 offset:4384
	ds_read_b32 v251, v154 offset:6560
	ds_read_b32 v252, v154 offset:8736
	ds_read_b32 v253, v154 offset:10912
	ds_read_b32 v156, v154 offset:13088
	ds_read_b32 v157, v154 offset:15264
	global_store_dwordx4 v155, v[146:149], s[4:5]
	s_waitcnt lgkmcnt(0)
	s_nop 0
	v_cvt_pk_bf16_f32 v146, v248, v249
	s_waitcnt lgkmcnt(0)
	v_cvt_pk_bf16_f32 v147, v250, v251
	s_waitcnt lgkmcnt(0)
	v_cvt_pk_bf16_f32 v148, v252, v253
	s_waitcnt lgkmcnt(0)
	v_cvt_pk_bf16_f32 v149, v156, v157
	ds_read_b32 v248, v154 offset:64
	ds_read_b32 v249, v154 offset:2240
	ds_read_b32 v250, v154 offset:4416
	ds_read_b32 v251, v154 offset:6592
	ds_read_b32 v252, v154 offset:8768
	ds_read_b32 v253, v154 offset:10944
	ds_read_b32 v156, v154 offset:13120
	ds_read_b32 v157, v154 offset:15296
	global_store_dwordx4 v155, v[146:149], s[12:13]
	s_add_u32 s12, s12, s10
	s_addc_u32 s13, s13, s11
	s_waitcnt lgkmcnt(0)
; #define GAS __attribute__((address_space(1)))
; #define LAS __attribute__((address_space(3)))
; __device__ __forceinline__ unsigned cvt_pk_bf16(float lo, float hi) { unsigned r; asm volatile("v_cvt_pk_bf16_f32 %0, %1, %2" : "=v"(r) : "v"(lo), "v"(hi)); return r; }
; #define LDS_WAIT() asm volatile("s_waitcnt lgkmcnt(0)" ::: "memory")
; __device__ __forceinline__ void p0_finish(const P0Item& it, const f32x4 (&w)[16], LAS float* scr, int lane) {
;     ...
;     const unsigned soff = (unsigned)(((lane >> 3) * it.K + 8 * (lane & 7)) * 2);
; #pragma unroll
;     for (int j = 0; j < 8; ++j) { const int n = (lane >> 3) + 8 * j, c = lane & 7; const LAS float* sp = scr + (8 * c) * 68 + n;
;         u32x4 o; o.x = cvt_pk_bf16(sp[0 * 68], sp[1 * 68]); o.y = cvt_pk_bf16(sp[2 * 68], sp[3 * 68]); o.z = cvt_pk_bf16(sp[4 * 68], sp[5 * 68]); o.w = cvt_pk_bf16(sp[6 * 68], sp[7 * 68]);
;         *(GAS u32x4*)((char*)(it.dst + (size_t)(8 * j) * it.K) + soff) = o; }
;     LDS_WAIT(); asm volatile("" ::: "memory");
	v_cvt_pk_bf16_f32 v146, v248, v249
	s_waitcnt lgkmcnt(0)
	v_cvt_pk_bf16_f32 v147, v250, v251
	s_waitcnt lgkmcnt(0)
	v_cvt_pk_bf16_f32 v148, v252, v253
	s_waitcnt lgkmcnt(0)
	v_cvt_pk_bf16_f32 v149, v156, v157
	ds_read_b32 v248, v154 offset:96
	ds_read_b32 v249, v154 offset:2272
	ds_read_b32 v250, v154 offset:4448
	ds_read_b32 v251, v154 offset:6624
	ds_read_b32 v252, v154 offset:8800
	ds_read_b32 v253, v154 offset:10976
	ds_read_b32 v156, v154 offset:13152
	ds_read_b32 v157, v154 offset:15328
	global_store_dwordx4 v155, v[146:149], s[12:13]
	s_add_u32 s12, s12, s10
	s_addc_u32 s13, s13, s11
	s_waitcnt lgkmcnt(0)
	v_cvt_pk_bf16_f32 v146, v248, v249
	s_waitcnt lgkmcnt(0)
	v_cvt_pk_bf16_f32 v147, v250, v251
	s_waitcnt lgkmcnt(0)
	v_cvt_pk_bf16_f32 v148, v252, v253
	s_waitcnt lgkmcnt(0)
	v_cvt_pk_bf16_f32 v149, v156, v157
	ds_read_b32 v248, v154 offset:128
	ds_read_b32 v249, v154 offset:2304
	ds_read_b32 v250, v154 offset:4480
	ds_read_b32 v251, v154 offset:6656
	ds_read_b32 v252, v154 offset:8832
	ds_read_b32 v253, v154 offset:11008
	ds_read_b32 v156, v154 offset:13184
	ds_read_b32 v157, v154 offset:15360
	global_store_dwordx4 v155, v[146:149], s[12:13]
	s_add_u32 s12, s12, s10
	s_addc_u32 s13, s13, s11
	s_waitcnt lgkmcnt(0)
	v_cvt_pk_bf16_f32 v146, v248, v249
	s_waitcnt lgkmcnt(0)
	v_cvt_pk_bf16_f32 v147, v250, v251
	s_waitcnt lgkmcnt(0)
	v_cvt_pk_bf16_f32 v148, v252, v253
	s_waitcnt lgkmcnt(0)
	v_cvt_pk_bf16_f32 v149, v156, v157
	ds_read_b32 v156, v154 offset:160
	ds_read_b32 v157, v154 offset:2336
	global_store_dwordx4 v155, v[146:149], s[12:13]
	s_waitcnt lgkmcnt(0)
	v_cvt_pk_bf16_f32 v156, v156, v157
	ds_read_b32 v146, v154 offset:4512
	ds_read_b32 v147, v154 offset:6688
	s_waitcnt lgkmcnt(0)
	v_cvt_pk_bf16_f32 v157, v146, v147
	ds_read_b32 v146, v154 offset:8864
	ds_read_b32 v147, v154 offset:11040
	s_waitcnt lgkmcnt(0)
	v_cvt_pk_bf16_f32 v158, v146, v147
	v_add_u32_e32 v146, 0x600, v154
	ds_read_b32 v148, v154 offset:13216
	ds_read_b32 v149, v154 offset:15392
	s_add_u32 s12, s12, s10
	s_waitcnt lgkmcnt(0)
	v_cvt_pk_bf16_f32 v159, v148, v149
	ds_read_b32 v248, v154 offset:192
	ds_read_b32 v249, v154 offset:2368
	ds_read_b32 v250, v154 offset:4544
	ds_read_b32 v251, v154 offset:6720
	ds_read_b32 v252, v154 offset:8896
	ds_read_b32 v253, v154 offset:11072
	ds_read_b32 v148, v154 offset:13248
	ds_read_b32 v149, v154 offset:15424
	s_addc_u32 s13, s13, s11
	global_store_dwordx4 v155, v[156:159], s[12:13]
	s_add_u32 s12, s12, s10
	s_addc_u32 s13, s13, s11
	s_waitcnt lgkmcnt(0)
	v_cvt_pk_bf16_f32 v156, v248, v249
	s_waitcnt lgkmcnt(0)
	v_cvt_pk_bf16_f32 v157, v250, v251
	s_waitcnt lgkmcnt(0)
	v_cvt_pk_bf16_f32 v158, v252, v253
	s_waitcnt lgkmcnt(0)
	v_cvt_pk_bf16_f32 v159, v148, v149
	ds_read_b32 v248, v154 offset:224
	ds_read_b32 v249, v154 offset:2400
	ds_read_b32 v250, v154 offset:4576
	ds_read_b32 v251, v154 offset:6752
	ds_read_b32 v252, v154 offset:8928
	ds_read_b32 v253, v154 offset:11104
	ds_read_b32 v148, v154 offset:13280
	ds_read_b32 v149, v154 offset:15456
	v_add_u32_e32 v147, 0x200, v154
	global_store_dwordx4 v155, v[156:159], s[12:13]
	s_add_u32 s10, s12, s10
	s_addc_u32 s11, s13, s11
	s_waitcnt lgkmcnt(0)
	v_cvt_pk_bf16_f32 v156, v248, v249
	s_waitcnt lgkmcnt(0)
	v_cvt_pk_bf16_f32 v157, v250, v251
	s_waitcnt lgkmcnt(0)
	v_cvt_pk_bf16_f32 v158, v252, v253
	s_waitcnt lgkmcnt(0)
	v_cvt_pk_bf16_f32 v159, v148, v149
	global_store_dwordx4 v155, v[156:159], s[10:11]
	s_waitcnt lgkmcnt(0)
	s_cmp_gt_u32 s26, 13
	s_cselect_b64 s[10:11], -1, 0
	s_and_b64 vcc, exec, s[10:11]
	s_cbranch_vccnz .LBB0_182
	s_add_i32 s9, s22, 0xffff1000
	s_cmpk_gt_i32 s9, 0xfff
	s_mov_b64 s[12:13], -1
	s_cbranch_scc0 .LBB0_214
	s_cmpk_gt_u32 s9, 0x1fff
	s_cbranch_scc0 .LBB0_211
	s_cmpk_gt_u32 s9, 0x2fff
	s_cbranch_scc0 .LBB0_208
	s_add_i32 s0, s23, 0x400
	s_and_b32 s27, s0, 0xfc0
	s_cmpk_gt_u32 s9, 0x3fff
	s_cbranch_scc0 .LBB0_205
	s_and_b32 s0, s9, 0x7fffffc0
	s_addk_i32 s0, 0xc000
	s_lshl_b64 s[4:5], s[0:1], 14
	v_lshl_add_u64 v[2:3], v[142:143], 0, s[4:5]
	s_lshl_b32 s4, s27, 2
	s_mov_b32 s5, s1
	v_lshl_add_u64 v[2:3], v[2:3], 0, s[4:5]
	s_lshl_b32 s4, s27, 15
	v_readlane_b32 s12, v254, 13
	v_readlane_b32 s13, v254, 14
	s_add_u32 s12, s12, s4
	s_addc_u32 s13, s13, 0
	s_lshl_b64 s[4:5], s[0:1], 1
	s_add_u32 s4, s12, s4
	s_addc_u32 s5, s13, s5
	s_mov_b64 s[12:13], 0

; #define GAS __attribute__((address_space(1)))
; #define LAS __attribute__((address_space(3)))
; __device__ __forceinline__ unsigned cvt_pk_bf16(float lo, float hi) { unsigned r; asm volatile("v_cvt_pk_bf16_f32 %0, %1, %2" : "=v"(r) : "v"(lo), "v"(hi)); return r; }
; #define LDS_WAIT() asm volatile("s_waitcnt lgkmcnt(0)" ::: "memory")
; __device__ __forceinline__ void p0_finish(const P0Item& it, const f32x4 (&w)[16], LAS float* scr, int lane) {
;     ...
;     const unsigned soff = (unsigned)(((lane >> 3) * it.K + 8 * (lane & 7)) * 2);
; #pragma unroll
;     for (int j = 0; j < 8; ++j) { const int n = (lane >> 3) + 8 * j, c = lane & 7; const LAS float* sp = scr + (8 * c) * 68 + n;
;         u32x4 o; o.x = cvt_pk_bf16(sp[0 * 68], sp[1 * 68]); o.y = cvt_pk_bf16(sp[2 * 68], sp[3 * 68]); o.z = cvt_pk_bf16(sp[4 * 68], sp[5 * 68]); o.w = cvt_pk_bf16(sp[6 * 68], sp[7 * 68]);
;         *(GAS u32x4*)((char*)(it.dst + (size_t)(8 * j) * it.K) + soff) = o; }
;     LDS_WAIT(); asm volatile("" ::: "memory");
.LBB0_259:
	s_or_b64 exec, exec, s[24:25]
	s_waitcnt vmcnt(0)
	ds_write_b128 v151, v[66:69] offset:10608
	s_waitcnt lgkmcnt(0)
	s_lshl_b64 s[12:13], s[12:13], 13
	s_add_u32 s12, s33, s12
	ds_read_b32 v248, v155
	ds_read_b32 v249, v155 offset:2176
	ds_read_b32 v250, v155 offset:4352
	ds_read_b32 v251, v155 offset:6528
	ds_read_b32 v252, v155 offset:8704
	ds_read_b32 v253, v155 offset:10880
	ds_read_b32 v70, v155 offset:13056
	ds_read_b32 v71, v155 offset:15232
	s_addc_u32 s13, s60, s13
	s_lshl_b64 s[10:11], s[10:11], 1
	s_waitcnt lgkmcnt(0)
	v_cvt_pk_bf16_f32 v66, v248, v249
	s_add_u32 s10, s12, s10
	s_waitcnt lgkmcnt(0)
	v_cvt_pk_bf16_f32 v67, v250, v251
	s_addc_u32 s11, s13, s11
	s_waitcnt lgkmcnt(0)
	v_cvt_pk_bf16_f32 v68, v252, v253
	s_waitcnt lgkmcnt(0)
	v_cvt_pk_bf16_f32 v69, v70, v71
	v_lshl_add_u64 v[72:73], s[10:11], 0, v[144:145]
	ds_read_b32 v248, v155 offset:32
	ds_read_b32 v249, v155 offset:2208
	ds_read_b32 v250, v155 offset:4384
	ds_read_b32 v251, v155 offset:6560
	ds_read_b32 v252, v155 offset:8736
	ds_read_b32 v253, v155 offset:10912
	ds_read_b32 v70, v155 offset:13088
	ds_read_b32 v71, v155 offset:15264
	global_store_dwordx4 v[72:73], v[66:69], off
	v_add_co_u32_e32 v74, vcc, s44, v72
	s_waitcnt lgkmcnt(0)
	v_cvt_pk_bf16_f32 v66, v248, v249
	s_waitcnt lgkmcnt(0)
	v_cvt_pk_bf16_f32 v67, v250, v251
	s_waitcnt lgkmcnt(0)
	v_cvt_pk_bf16_f32 v68, v252, v253
	s_waitcnt lgkmcnt(0)
	v_cvt_pk_bf16_f32 v69, v70, v71
	v_addc_co_u32_e32 v75, vcc, 0, v73, vcc
	ds_read_b32 v248, v155 offset:64
	ds_read_b32 v249, v155 offset:2240
	ds_read_b32 v250, v155 offset:4416
	ds_read_b32 v251, v155 offset:6592
	ds_read_b32 v252, v155 offset:8768
	ds_read_b32 v253, v155 offset:10944
	ds_read_b32 v70, v155 offset:13120
	ds_read_b32 v71, v155 offset:15296
	global_store_dwordx4 v[74:75], v[66:69], off
	v_add_co_u32_e32 v74, vcc, s45, v72
	s_waitcnt lgkmcnt(0)
	v_cvt_pk_bf16_f32 v66, v248, v249
	s_waitcnt lgkmcnt(0)
	v_cvt_pk_bf16_f32 v67, v250, v251
	s_waitcnt lgkmcnt(0)
	v_cvt_pk_bf16_f32 v68, v252, v253
	s_waitcnt lgkmcnt(0)
	v_cvt_pk_bf16_f32 v69, v70, v71
	v_addc_co_u32_e32 v75, vcc, 0, v73, vcc
	ds_read_b32 v248, v155 offset:96
	ds_read_b32 v249, v155 offset:2272
	ds_read_b32 v250, v155 offset:4448
	ds_read_b32 v251, v155 offset:6624
	ds_read_b32 v252, v155 offset:8800
	ds_read_b32 v253, v155 offset:10976
	ds_read_b32 v70, v155 offset:13152
	ds_read_b32 v71, v155 offset:15328
	global_store_dwordx4 v[74:75], v[66:69], off
	v_add_co_u32_e32 v74, vcc, s46, v72
	s_waitcnt lgkmcnt(0)
	v_cvt_pk_bf16_f32 v66, v248, v249
	s_waitcnt lgkmcnt(0)
	v_cvt_pk_bf16_f32 v67, v250, v251
	s_waitcnt lgkmcnt(0)
	v_cvt_pk_bf16_f32 v68, v252, v253
	s_waitcnt lgkmcnt(0)
	v_cvt_pk_bf16_f32 v69, v70, v71
	v_addc_co_u32_e32 v75, vcc, 0, v73, vcc
	ds_read_b32 v248, v155 offset:128
	ds_read_b32 v249, v155 offset:2304
	ds_read_b32 v250, v155 offset:4480
	ds_read_b32 v251, v155 offset:6656
	ds_read_b32 v252, v155 offset:8832
	ds_read_b32 v253, v155 offset:11008
	ds_read_b32 v70, v155 offset:13184
	ds_read_b32 v71, v155 offset:15360
	global_store_dwordx4 v[74:75], v[66:69], off
	v_add_co_u32_e32 v74, vcc, s28, v72
	s_waitcnt lgkmcnt(0)
	v_cvt_pk_bf16_f32 v66, v248, v249
	s_waitcnt lgkmcnt(0)
	v_cvt_pk_bf16_f32 v67, v250, v251
	s_waitcnt lgkmcnt(0)
	v_cvt_pk_bf16_f32 v68, v252, v253
	s_waitcnt lgkmcnt(0)
	v_cvt_pk_bf16_f32 v69, v70, v71
	v_addc_co_u32_e32 v75, vcc, 0, v73, vcc
	ds_read_b32 v248, v155 offset:160
	ds_read_b32 v249, v155 offset:2336
	ds_read_b32 v250, v155 offset:4512
	ds_read_b32 v251, v155 offset:6688
	ds_read_b32 v252, v155 offset:8864
	ds_read_b32 v253, v155 offset:11040
	ds_read_b32 v70, v155 offset:13216
	ds_read_b32 v71, v155 offset:15392
	global_store_dwordx4 v[74:75], v[66:69], off
	v_add_co_u32_e32 v74, vcc, s47, v72
	s_waitcnt lgkmcnt(0)
	v_cvt_pk_bf16_f32 v66, v248, v249
	s_waitcnt lgkmcnt(0)
	v_cvt_pk_bf16_f32 v67, v250, v251
	s_waitcnt lgkmcnt(0)
	v_cvt_pk_bf16_f32 v68, v252, v253
	s_waitcnt lgkmcnt(0)
	v_cvt_pk_bf16_f32 v69, v70, v71
	v_addc_co_u32_e32 v75, vcc, 0, v73, vcc
	ds_read_b32 v248, v155 offset:192
	ds_read_b32 v249, v155 offset:2368
	ds_read_b32 v250, v155 offset:4544
	ds_read_b32 v251, v155 offset:6720
	ds_read_b32 v252, v155 offset:8896
	ds_read_b32 v253, v155 offset:11072
	ds_read_b32 v70, v155 offset:13248
	ds_read_b32 v71, v155 offset:15424
	global_store_dwordx4 v[74:75], v[66:69], off
	v_add_co_u32_e32 v74, vcc, s48, v72
	s_waitcnt lgkmcnt(0)
	v_cvt_pk_bf16_f32 v66, v248, v249
	s_waitcnt lgkmcnt(0)
	v_cvt_pk_bf16_f32 v67, v250, v251
	s_waitcnt lgkmcnt(0)
	v_cvt_pk_bf16_f32 v68, v252, v253
	s_waitcnt lgkmcnt(0)
	v_cvt_pk_bf16_f32 v69, v70, v71
	v_addc_co_u32_e32 v75, vcc, 0, v73, vcc
	ds_read_b32 v248, v155 offset:224
	ds_read_b32 v249, v155 offset:2400
	ds_read_b32 v250, v155 offset:4576
	ds_read_b32 v251, v155 offset:6752
	ds_read_b32 v252, v155 offset:8928
	ds_read_b32 v253, v155 offset:11104
	ds_read_b32 v70, v155 offset:13280
	ds_read_b32 v71, v155 offset:15456
	global_store_dwordx4 v[74:75], v[66:69], off
	v_add_co_u32_e32 v72, vcc, 0x70000, v72
	s_waitcnt lgkmcnt(0)
	v_cvt_pk_bf16_f32 v66, v248, v249
	s_waitcnt lgkmcnt(0)
	v_cvt_pk_bf16_f32 v67, v250, v251
	v_addc_co_u32_e32 v73, vcc, 0, v73, vcc
	s_waitcnt lgkmcnt(0)
	v_cvt_pk_bf16_f32 v68, v252, v253
	s_waitcnt lgkmcnt(0)
	v_cvt_pk_bf16_f32 v69, v70, v71
	global_store_dwordx4 v[72:73], v[66:69], off
	s_waitcnt lgkmcnt(0)
	s_add_i32 s42, s42, 2
	s_andn2_b64 vcc, exec, s[22:23]
	s_addk_i32 s43, 0x1000
	s_cbranch_vccz .LBB0_270

; #define GAS __attribute__((address_space(1)))
; #define LAS __attribute__((address_space(3)))
; __device__ __forceinline__ unsigned cvt_pk_bf16(float lo, float hi) { unsigned r; asm volatile("v_cvt_pk_bf16_f32 %0, %1, %2" : "=v"(r) : "v"(lo), "v"(hi)); return r; }
; #define LDS_WAIT() asm volatile("s_waitcnt lgkmcnt(0)" ::: "memory")
; __device__ __forceinline__ void p0_finish(const P0Item& it, const f32x4 (&w)[16], LAS float* scr, int lane) {
;     ...
;     LDS_WAIT(); asm volatile("" ::: "memory");
;     const unsigned soff = (unsigned)(((lane >> 3) * it.K + 8 * (lane & 7)) * 2);
; #pragma unroll
;     for (int j = 0; j < 8; ++j) { const int n = (lane >> 3) + 8 * j, c = lane & 7; const LAS float* sp = scr + (8 * c) * 68 + n;
;         u32x4 o; o.x = cvt_pk_bf16(sp[0 * 68], sp[1 * 68]); o.y = cvt_pk_bf16(sp[2 * 68], sp[3 * 68]); o.z = cvt_pk_bf16(sp[4 * 68], sp[5 * 68]); o.w = cvt_pk_bf16(sp[6 * 68], sp[7 * 68]);
;         *(GAS u32x4*)((char*)(it.dst + (size_t)(8 * j) * it.K) + soff) = o; }
;     LDS_WAIT(); asm volatile("" ::: "memory");
; template <class F> __device__ __forceinline__ void p0_pipe(int n, F desc, LAS float* scr, int lane) {
;     ...
;     for (int j = 0; j < n; j += 2) {
;         const bool hb_ = j + 1 < n; if (hb_) { b = desc(j + 1); p0_load(b, w1, lane); }
;         p0_finish(a, w0, scr, lane);
;         if (!hb_) break;
;         if (j + 2 < n) { a = desc(j + 2); p0_load(a, w0, lane); }
;         p0_finish(b, w1, scr, lane);
.LBB0_264:
	s_or_b64 exec, exec, s[22:23]
	ds_write_b128 v151, v[130:133] offset:10608
	s_waitcnt lgkmcnt(0)
	ds_read_b32 v248, v155
	ds_read_b32 v249, v155 offset:2176
	ds_read_b32 v250, v155 offset:4352
	ds_read_b32 v251, v155 offset:6528
	ds_read_b32 v252, v155 offset:8704
	ds_read_b32 v253, v155 offset:10880
	ds_read_b32 v132, v155 offset:13056
	ds_read_b32 v133, v155 offset:15232
	s_waitcnt lgkmcnt(0)
	v_cvt_pk_bf16_f32 v176, v248, v249
	v_add_u32_e32 v130, 0x400, v155
	s_waitcnt lgkmcnt(0)
	v_cvt_pk_bf16_f32 v177, v250, v251
	s_waitcnt lgkmcnt(0)
	v_cvt_pk_bf16_f32 v178, v252, v253
	s_waitcnt lgkmcnt(0)
	v_cvt_pk_bf16_f32 v179, v132, v133
	ds_read_b32 v248, v155 offset:32
	ds_read_b32 v249, v155 offset:2208
	ds_read_b32 v250, v155 offset:4384
	ds_read_b32 v251, v155 offset:6560
	ds_read_b32 v252, v155 offset:8736
	ds_read_b32 v253, v155 offset:10912
	ds_read_b32 v132, v155 offset:13088
	ds_read_b32 v133, v155 offset:15264
	v_lshl_add_u64 v[164:165], s[0:1], 0, v[144:145]
	global_store_dwordx4 v[164:165], v[176:179], off
	v_add_co_u32_e32 v180, vcc, s44, v164
	s_waitcnt lgkmcnt(0)
	v_cvt_pk_bf16_f32 v176, v248, v249
	s_waitcnt lgkmcnt(0)
	v_cvt_pk_bf16_f32 v177, v250, v251
	s_waitcnt lgkmcnt(0)
	v_cvt_pk_bf16_f32 v178, v252, v253
	s_waitcnt lgkmcnt(0)
	v_cvt_pk_bf16_f32 v179, v132, v133
	ds_read_b32 v248, v155 offset:64
	ds_read_b32 v249, v155 offset:2240
	ds_read_b32 v250, v155 offset:4416
	ds_read_b32 v251, v155 offset:6592
	ds_read_b32 v252, v155 offset:8768
	ds_read_b32 v253, v155 offset:10944
	ds_read_b32 v132, v155 offset:13120
	ds_read_b32 v133, v155 offset:15296
	v_addc_co_u32_e32 v181, vcc, 0, v165, vcc
	global_store_dwordx4 v[180:181], v[176:179], off
	v_add_co_u32_e32 v180, vcc, s45, v164
	s_waitcnt lgkmcnt(0)
	v_cvt_pk_bf16_f32 v176, v248, v249
	s_waitcnt lgkmcnt(0)
	v_cvt_pk_bf16_f32 v177, v250, v251
	s_waitcnt lgkmcnt(0)
	v_cvt_pk_bf16_f32 v178, v252, v253
	s_waitcnt lgkmcnt(0)
	v_cvt_pk_bf16_f32 v179, v132, v133
	ds_read_b32 v248, v155 offset:96
	ds_read_b32 v249, v155 offset:2272
	ds_read_b32 v250, v155 offset:4448
	ds_read_b32 v251, v155 offset:6624
	ds_read_b32 v252, v155 offset:8800
	ds_read_b32 v253, v155 offset:10976
	ds_read_b32 v132, v155 offset:13152
	ds_read_b32 v133, v155 offset:15328
	v_addc_co_u32_e32 v181, vcc, 0, v165, vcc
	global_store_dwordx4 v[180:181], v[176:179], off
	v_add_co_u32_e32 v180, vcc, s46, v164
	s_waitcnt lgkmcnt(0)
	v_cvt_pk_bf16_f32 v176, v248, v249
	s_waitcnt lgkmcnt(0)
	v_cvt_pk_bf16_f32 v177, v250, v251
	s_waitcnt lgkmcnt(0)
	v_cvt_pk_bf16_f32 v178, v252, v253
	s_waitcnt lgkmcnt(0)
	v_cvt_pk_bf16_f32 v179, v132, v133
	ds_read_b32 v248, v155 offset:128
	ds_read_b32 v249, v155 offset:2304
	ds_read_b32 v250, v155 offset:4480
	ds_read_b32 v251, v155 offset:6656
	ds_read_b32 v252, v155 offset:8832
	ds_read_b32 v253, v155 offset:11008
	ds_read_b32 v132, v155 offset:13184
	ds_read_b32 v133, v155 offset:15360
	v_addc_co_u32_e32 v181, vcc, 0, v165, vcc
	global_store_dwordx4 v[180:181], v[176:179], off
	v_add_co_u32_e32 v180, vcc, s28, v164
	s_waitcnt lgkmcnt(0)
	v_cvt_pk_bf16_f32 v176, v248, v249
	s_waitcnt lgkmcnt(0)
	v_cvt_pk_bf16_f32 v177, v250, v251
	s_waitcnt lgkmcnt(0)
	v_cvt_pk_bf16_f32 v178, v252, v253
	s_waitcnt lgkmcnt(0)
	v_cvt_pk_bf16_f32 v179, v132, v133
	ds_read_b32 v248, v155 offset:160
	ds_read_b32 v249, v155 offset:2336
	ds_read_b32 v250, v155 offset:4512
	ds_read_b32 v251, v155 offset:6688
	ds_read_b32 v252, v155 offset:8864
	ds_read_b32 v253, v155 offset:11040
	ds_read_b32 v132, v155 offset:13216
	ds_read_b32 v133, v155 offset:15392
	v_addc_co_u32_e32 v181, vcc, 0, v165, vcc
	global_store_dwordx4 v[180:181], v[176:179], off
	v_add_u32_e32 v131, 0x600, v155
	v_add_co_u32_e32 v180, vcc, s47, v164
	s_waitcnt lgkmcnt(0)
	v_cvt_pk_bf16_f32 v176, v248, v249
	s_waitcnt lgkmcnt(0)
	v_cvt_pk_bf16_f32 v177, v250, v251
	s_waitcnt lgkmcnt(0)
	v_cvt_pk_bf16_f32 v178, v252, v253
	s_waitcnt lgkmcnt(0)
	v_cvt_pk_bf16_f32 v179, v132, v133
	ds_read_b32 v132, v155 offset:192
	ds_read_b32 v133, v155 offset:2368
	v_addc_co_u32_e32 v181, vcc, 0, v165, vcc
	global_store_dwordx4 v[180:181], v[176:179], off
	v_add_co_u32_e32 v184, vcc, s48, v164
	s_waitcnt lgkmcnt(0)
	v_cvt_pk_bf16_f32 v176, v132, v133
	ds_read_b32 v132, v155 offset:4544
	ds_read_b32 v133, v155 offset:6720
	s_waitcnt lgkmcnt(0)
	v_cvt_pk_bf16_f32 v177, v132, v133
	ds_read_b32 v132, v155 offset:8896
	ds_read_b32 v133, v155 offset:11072
	s_waitcnt lgkmcnt(0)
	v_cvt_pk_bf16_f32 v178, v132, v133
	ds_read_b32 v180, v155 offset:13248
	ds_read_b32 v181, v155 offset:15424
	v_add_u32_e32 v132, 0x200, v155
	s_waitcnt lgkmcnt(0)
	v_cvt_pk_bf16_f32 v179, v180, v181
	v_addc_co_u32_e32 v185, vcc, 0, v165, vcc
	ds_read_b32 v248, v155 offset:224
	ds_read_b32 v249, v155 offset:2400
	ds_read_b32 v250, v155 offset:4576
	ds_read_b32 v251, v155 offset:6752
	ds_read_b32 v252, v155 offset:8928
	ds_read_b32 v253, v155 offset:11104
	ds_read_b32 v180, v155 offset:13280
	ds_read_b32 v181, v155 offset:15456
	global_store_dwordx4 v[184:185], v[176:179], off
	v_add_co_u32_e32 v164, vcc, 0x70000, v164
	s_waitcnt lgkmcnt(0)
	v_cvt_pk_bf16_f32 v176, v248, v249
	s_waitcnt lgkmcnt(0)
	v_cvt_pk_bf16_f32 v177, v250, v251
	v_addc_co_u32_e32 v165, vcc, 0, v165, vcc
	s_waitcnt lgkmcnt(0)
	v_cvt_pk_bf16_f32 v178, v252, v253
	s_waitcnt lgkmcnt(0)
	v_cvt_pk_bf16_f32 v179, v180, v181
	global_store_dwordx4 v[164:165], v[176:179], off
	s_waitcnt lgkmcnt(0)
	s_cmp_gt_u32 s42, 5
	s_cselect_b64 s[22:23], -1, 0
	s_and_b64 vcc, exec, s[22:23]
	s_cbranch_vccz .LBB0_267
	s_and_saveexec_b64 s[24:25], s[6:7]
	s_xor_b64 s[24:25], exec, s[24:25]
	s_cbranch_execnz .LBB0_268

; #define GAS __attribute__((address_space(1)))
; #define LAS __attribute__((address_space(3)))
; __device__ __forceinline__ unsigned cvt_pk_bf16(float lo, float hi) { unsigned r; asm volatile("v_cvt_pk_bf16_f32 %0, %1, %2" : "=v"(r) : "v"(lo), "v"(hi)); return r; }
; #define LDS_WAIT() asm volatile("s_waitcnt lgkmcnt(0)" ::: "memory")
; __device__ __forceinline__ void p0_finish(const P0Item& it, const f32x4 (&w)[16], LAS float* scr, int lane) {
;     ...
;         for (int i = 0; i < 16; ++i) *(LAS f32x4*)(scr + (kr + 4 * i) * 68 + c4) = w[i]; }
;     LDS_WAIT(); asm volatile("" ::: "memory");
;     const unsigned soff = (unsigned)(((lane >> 3) * it.K + 8 * (lane & 7)) * 2);
; #pragma unroll
;     for (int j = 0; j < 8; ++j) { const int n = (lane >> 3) + 8 * j, c = lane & 7; const LAS float* sp = scr + (8 * c) * 68 + n;
;         u32x4 o; o.x = cvt_pk_bf16(sp[0 * 68], sp[1 * 68]); o.y = cvt_pk_bf16(sp[2 * 68], sp[3 * 68]); o.z = cvt_pk_bf16(sp[4 * 68], sp[5 * 68]); o.w = cvt_pk_bf16(sp[6 * 68], sp[7 * 68]);
;         *(GAS u32x4*)((char*)(it.dst + (size_t)(8 * j) * it.K) + soff) = o; }
;     LDS_WAIT(); asm volatile("" ::: "memory");
; template <class F> __device__ __forceinline__ void p0_pipe(int n, F desc, LAS float* scr, int lane) {
;     ...
;     for (int j = 0; j < n; j += 2) {
;         const bool hb_ = j + 1 < n; if (hb_) { b = desc(j + 1); p0_load(b, w1, lane); }
;         p0_finish(a, w0, scr, lane);
;         if (!hb_) break;
;         if (j + 2 < n) { a = desc(j + 2); p0_load(a, w0, lane); }
;         p0_finish(b, w1, scr, lane);
.LBB0_294:
	ds_write_b128 v151, v[66:69]
	ds_write_b128 v151, v[70:73] offset:8704
	ds_write_b128 v151, v[74:77] offset:272
	ds_write_b128 v151, v[78:81] offset:8976
	ds_write_b128 v151, v[82:85] offset:544
	ds_write_b128 v151, v[86:89] offset:9248
	ds_write_b128 v151, v[90:93] offset:816
	ds_write_b128 v151, v[94:97] offset:9520
	ds_write_b128 v151, v[98:101] offset:1088
	ds_write_b128 v151, v[102:105] offset:9792
	ds_write_b128 v151, v[106:109] offset:1360
	ds_write_b128 v151, v[110:113] offset:10064
	ds_write_b128 v151, v[114:117] offset:1632
	ds_write_b128 v151, v[118:121] offset:10336
	ds_write_b128 v151, v[122:125] offset:1904
	ds_write_b128 v151, v[126:129] offset:10608
	s_waitcnt lgkmcnt(0)
	ds_read_b32 v248, v155
	ds_read_b32 v249, v155 offset:2176
	ds_read_b32 v250, v155 offset:4352
	ds_read_b32 v251, v155 offset:6528
	ds_read_b32 v252, v155 offset:8704
	ds_read_b32 v253, v155 offset:10880
	ds_read_b32 v70, v155 offset:13056
	ds_read_b32 v71, v155 offset:15232
	s_waitcnt lgkmcnt(0)
	v_cvt_pk_bf16_f32 v66, v248, v249
	v_mul_lo_u32 v72, s10, v152
	s_waitcnt lgkmcnt(0)
	v_cvt_pk_bf16_f32 v67, v250, v251
	v_or_b32_e32 v72, v72, v154
	s_waitcnt lgkmcnt(0)
	v_cvt_pk_bf16_f32 v68, v252, v253
	s_waitcnt lgkmcnt(0)
	v_cvt_pk_bf16_f32 v69, v70, v71
	v_lshlrev_b32_e32 v72, 1, v72
	s_mov_b32 s11, s1
	ds_read_b32 v248, v155 offset:32
	ds_read_b32 v249, v155 offset:2208
	ds_read_b32 v250, v155 offset:4384
	ds_read_b32 v251, v155 offset:6560
	ds_read_b32 v252, v155 offset:8736
	ds_read_b32 v253, v155 offset:10912
	ds_read_b32 v70, v155 offset:13088
	ds_read_b32 v71, v155 offset:15264
	global_store_dwordx4 v72, v[66:69], s[8:9]
	s_lshl_b64 s[10:11], s[10:11], 4
	s_add_u32 s8, s8, s10
	s_waitcnt lgkmcnt(0)
	v_cvt_pk_bf16_f32 v66, v248, v249
	s_waitcnt lgkmcnt(0)
	v_cvt_pk_bf16_f32 v67, v250, v251
	s_waitcnt lgkmcnt(0)
	v_cvt_pk_bf16_f32 v68, v252, v253
	s_waitcnt lgkmcnt(0)
	v_cvt_pk_bf16_f32 v69, v70, v71
	s_addc_u32 s9, s9, s11
	ds_read_b32 v248, v155 offset:64
	ds_read_b32 v249, v155 offset:2240
	ds_read_b32 v250, v155 offset:4416
	ds_read_b32 v251, v155 offset:6592
	ds_read_b32 v252, v155 offset:8768
	ds_read_b32 v253, v155 offset:10944
	ds_read_b32 v70, v155 offset:13120
	ds_read_b32 v71, v155 offset:15296
	global_store_dwordx4 v72, v[66:69], s[8:9]
	s_add_u32 s8, s8, s10
	s_addc_u32 s9, s9, s11
	s_waitcnt lgkmcnt(0)
	v_cvt_pk_bf16_f32 v66, v248, v249
	s_waitcnt lgkmcnt(0)
	v_cvt_pk_bf16_f32 v67, v250, v251
	s_waitcnt lgkmcnt(0)
	v_cvt_pk_bf16_f32 v68, v252, v253
	s_waitcnt lgkmcnt(0)
	v_cvt_pk_bf16_f32 v69, v70, v71
	ds_read_b32 v248, v155 offset:96
	ds_read_b32 v249, v155 offset:2272
	ds_read_b32 v250, v155 offset:4448
	ds_read_b32 v251, v155 offset:6624
	ds_read_b32 v252, v155 offset:8800
	ds_read_b32 v253, v155 offset:10976
	ds_read_b32 v70, v155 offset:13152
	ds_read_b32 v71, v155 offset:15328
	global_store_dwordx4 v72, v[66:69], s[8:9]
	s_add_u32 s8, s8, s10
	s_addc_u32 s9, s9, s11
	s_waitcnt lgkmcnt(0)
	v_cvt_pk_bf16_f32 v66, v248, v249
	s_waitcnt lgkmcnt(0)
	v_cvt_pk_bf16_f32 v67, v250, v251
	s_waitcnt lgkmcnt(0)
	v_cvt_pk_bf16_f32 v68, v252, v253
	s_waitcnt lgkmcnt(0)
	v_cvt_pk_bf16_f32 v69, v70, v71
	ds_read_b32 v248, v155 offset:128
	ds_read_b32 v249, v155 offset:2304
	ds_read_b32 v250, v155 offset:4480
	ds_read_b32 v251, v155 offset:6656
	ds_read_b32 v252, v155 offset:8832
	ds_read_b32 v253, v155 offset:11008
	ds_read_b32 v70, v155 offset:13184
	ds_read_b32 v71, v155 offset:15360
	global_store_dwordx4 v72, v[66:69], s[8:9]
	s_add_u32 s8, s8, s10
	s_addc_u32 s9, s9, s11
	s_waitcnt lgkmcnt(0)
	v_cvt_pk_bf16_f32 v66, v248, v249
	s_waitcnt lgkmcnt(0)
	v_cvt_pk_bf16_f32 v67, v250, v251
	s_waitcnt lgkmcnt(0)
	v_cvt_pk_bf16_f32 v68, v252, v253
	s_waitcnt lgkmcnt(0)
	v_cvt_pk_bf16_f32 v69, v70, v71
	ds_read_b32 v248, v155 offset:160
	ds_read_b32 v249, v155 offset:2336
	ds_read_b32 v250, v155 offset:4512
	ds_read_b32 v251, v155 offset:6688
	ds_read_b32 v252, v155 offset:8864
	ds_read_b32 v253, v155 offset:11040
	ds_read_b32 v70, v155 offset:13216
	ds_read_b32 v71, v155 offset:15392
	global_store_dwordx4 v72, v[66:69], s[8:9]
	s_add_u32 s8, s8, s10
	s_addc_u32 s9, s9, s11
	s_waitcnt lgkmcnt(0)
	v_cvt_pk_bf16_f32 v66, v248, v249
	s_waitcnt lgkmcnt(0)
	v_cvt_pk_bf16_f32 v67, v250, v251
	s_waitcnt lgkmcnt(0)
	v_cvt_pk_bf16_f32 v68, v252, v253
	s_waitcnt lgkmcnt(0)
	v_cvt_pk_bf16_f32 v69, v70, v71
	ds_read_b32 v248, v155 offset:192
	ds_read_b32 v249, v155 offset:2368
	ds_read_b32 v250, v155 offset:4544
	ds_read_b32 v251, v155 offset:6720
	ds_read_b32 v252, v155 offset:8896
	ds_read_b32 v253, v155 offset:11072
	ds_read_b32 v70, v155 offset:13248
	ds_read_b32 v71, v155 offset:15424
	global_store_dwordx4 v72, v[66:69], s[8:9]
	s_add_u32 s8, s8, s10
	s_addc_u32 s9, s9, s11
	s_waitcnt lgkmcnt(0)
	v_cvt_pk_bf16_f32 v66, v248, v249
	s_waitcnt lgkmcnt(0)
	v_cvt_pk_bf16_f32 v67, v250, v251
	s_waitcnt lgkmcnt(0)
	v_cvt_pk_bf16_f32 v68, v252, v253
	s_waitcnt lgkmcnt(0)
	v_cvt_pk_bf16_f32 v69, v70, v71
	ds_read_b32 v248, v155 offset:224
	ds_read_b32 v249, v155 offset:2400
	ds_read_b32 v250, v155 offset:4576
	ds_read_b32 v251, v155 offset:6752
	ds_read_b32 v252, v155 offset:8928
	ds_read_b32 v253, v155 offset:11104
	ds_read_b32 v70, v155 offset:13280
	ds_read_b32 v71, v155 offset:15456
	global_store_dwordx4 v72, v[66:69], s[8:9]
	s_add_u32 s8, s8, s10
	s_addc_u32 s9, s9, s11
	s_waitcnt lgkmcnt(0)
	v_cvt_pk_bf16_f32 v66, v248, v249
	s_waitcnt lgkmcnt(0)
	v_cvt_pk_bf16_f32 v67, v250, v251
	s_waitcnt lgkmcnt(0)
	v_cvt_pk_bf16_f32 v68, v252, v253
	s_waitcnt lgkmcnt(0)
	v_cvt_pk_bf16_f32 v69, v70, v71
	global_store_dwordx4 v72, v[66:69], s[8:9]
	s_waitcnt lgkmcnt(0)
	s_add_i32 s28, s28, 2
	s_add_i32 s24, s24, 16
	s_andn2_b64 vcc, exec, s[12:13]
	s_addk_i32 s25, 0x400
	s_cbranch_vccz .LBB0_328

; #define GAS __attribute__((address_space(1)))
; #define LAS __attribute__((address_space(3)))
; __device__ __forceinline__ unsigned cvt_pk_bf16(float lo, float hi) { unsigned r; asm volatile("v_cvt_pk_bf16_f32 %0, %1, %2" : "=v"(r) : "v"(lo), "v"(hi)); return r; }
; #define LDS_WAIT() asm volatile("s_waitcnt lgkmcnt(0)" ::: "memory")
; __device__ __forceinline__ void p0_load(const P0Item& it, f32x4 (&w)[16], int lane) {
;     const unsigned voff = (unsigned)(((lane >> 4) * it.ldw + (lane & 15) * 4) * 4);
; #pragma unroll
;     for (int i = 0; i < 16; ++i) w[i] = __builtin_nontemporal_load((const f32x4*)((const char*)(it.src + (size_t)(4 * i) * it.ldw) + voff));
; }
; __device__ __forceinline__ void p0_finish(const P0Item& it, const f32x4 (&w)[16], LAS float* scr, int lane) {
;     ...
;         for (int i = 0; i < 16; ++i) *(LAS f32x4*)(scr + (kr + 4 * i) * 68 + c4) = w[i]; }
;     LDS_WAIT(); asm volatile("" ::: "memory");
;     const unsigned soff = (unsigned)(((lane >> 3) * it.K + 8 * (lane & 7)) * 2);
; #pragma unroll
;     for (int j = 0; j < 8; ++j) { const int n = (lane >> 3) + 8 * j, c = lane & 7; const LAS float* sp = scr + (8 * c) * 68 + n;
;         u32x4 o; o.x = cvt_pk_bf16(sp[0 * 68], sp[1 * 68]); o.y = cvt_pk_bf16(sp[2 * 68], sp[3 * 68]); o.z = cvt_pk_bf16(sp[4 * 68], sp[5 * 68]); o.w = cvt_pk_bf16(sp[6 * 68], sp[7 * 68]);
;         *(GAS u32x4*)((char*)(it.dst + (size_t)(8 * j) * it.K) + soff) = o; }
;     LDS_WAIT(); asm volatile("" ::: "memory");
; template <class F> __device__ __forceinline__ void p0_pipe(int n, F desc, LAS float* scr, int lane) {
;     ...
;         if (j + 2 < n) { a = desc(j + 2); p0_load(a, w0, lane); }
;         p0_finish(b, w1, scr, lane);
.LBB0_311:
	v_lshl_add_u64 v[122:123], v[66:67], 0, v[144:145]
	v_add_co_u32_e32 v70, vcc, 0x10000, v122
	v_add_u32_e32 v137, 0x400, v155
	s_nop 0
	v_addc_co_u32_e32 v71, vcc, 0, v123, vcc
	v_add_co_u32_e32 v74, vcc, 0x20000, v122
	flat_load_dwordx4 v[66:69], v[122:123] nt
	s_nop 0
	flat_load_dwordx4 v[70:73], v[70:71] nt
	v_addc_co_u32_e32 v75, vcc, 0, v123, vcc
	v_add_co_u32_e32 v78, vcc, 0x30000, v122
	v_mul_lo_u32 v158, s0, v152
	s_nop 0
	v_addc_co_u32_e32 v79, vcc, 0, v123, vcc
	v_add_co_u32_e32 v82, vcc, 0x40000, v122
	flat_load_dwordx4 v[74:77], v[74:75] nt
	s_nop 0
	flat_load_dwordx4 v[78:81], v[78:79] nt
	v_addc_co_u32_e32 v83, vcc, 0, v123, vcc
	v_add_co_u32_e32 v86, vcc, 0x50000, v122
	v_add_lshl_u32 v158, v158, v154, 1
	s_nop 0
	v_addc_co_u32_e32 v87, vcc, 0, v123, vcc
	v_add_co_u32_e32 v90, vcc, 0x60000, v122
	flat_load_dwordx4 v[82:85], v[82:83] nt
	s_nop 0
	flat_load_dwordx4 v[86:89], v[86:87] nt
	v_addc_co_u32_e32 v91, vcc, 0, v123, vcc
	v_add_co_u32_e32 v94, vcc, 0x70000, v122
	s_lshl_b64 s[12:13], s[0:1], 4
	s_nop 0
	v_addc_co_u32_e32 v95, vcc, 0, v123, vcc
	v_add_co_u32_e32 v98, vcc, 0x80000, v122
	flat_load_dwordx4 v[90:93], v[90:91] nt
	s_nop 0
	flat_load_dwordx4 v[94:97], v[94:95] nt
	v_addc_co_u32_e32 v99, vcc, 0, v123, vcc
	v_add_co_u32_e32 v102, vcc, 0x90000, v122
	s_add_u32 s22, s6, s12
	s_nop 0
	v_addc_co_u32_e32 v103, vcc, 0, v123, vcc
	v_add_co_u32_e32 v106, vcc, 0xa0000, v122
	flat_load_dwordx4 v[98:101], v[98:99] nt
	s_nop 0
	flat_load_dwordx4 v[102:105], v[102:103] nt
	v_addc_co_u32_e32 v107, vcc, 0, v123, vcc
	v_add_co_u32_e32 v110, vcc, 0xb0000, v122
	s_addc_u32 s23, s7, s13
	s_nop 0
	v_addc_co_u32_e32 v111, vcc, 0, v123, vcc
	v_add_co_u32_e32 v114, vcc, 0xc0000, v122
	flat_load_dwordx4 v[106:109], v[106:107] nt
	s_nop 0
	flat_load_dwordx4 v[110:113], v[110:111] nt
	v_addc_co_u32_e32 v115, vcc, 0, v123, vcc
	v_add_co_u32_e32 v118, vcc, 0xd0000, v122
	s_nop 1
	v_addc_co_u32_e32 v119, vcc, 0, v123, vcc
	v_add_co_u32_e32 v124, vcc, 0xe0000, v122
	flat_load_dwordx4 v[114:117], v[114:115] nt
	s_nop 0
	flat_load_dwordx4 v[118:121], v[118:119] nt
	v_addc_co_u32_e32 v125, vcc, 0, v123, vcc
	v_add_co_u32_e32 v126, vcc, 0xf0000, v122
	s_nop 1
	v_addc_co_u32_e32 v127, vcc, 0, v123, vcc
	flat_load_dwordx4 v[122:125], v[124:125] nt
	s_nop 0
	flat_load_dwordx4 v[126:129], v[126:127] nt
	s_waitcnt vmcnt(0) lgkmcnt(0)
	ds_write_b128 v151, v[2:5]
	ds_write_b128 v151, v[6:9] offset:8704
	ds_write_b128 v151, v[10:13] offset:272
	ds_write_b128 v151, v[14:17] offset:8976
	ds_write_b128 v151, v[18:21] offset:544
	ds_write_b128 v151, v[22:25] offset:9248
	ds_write_b128 v151, v[26:29] offset:816
	ds_write_b128 v151, v[30:33] offset:9520
	ds_write_b128 v151, v[34:37] offset:1088
	ds_write_b128 v151, v[38:41] offset:9792
	ds_write_b128 v151, v[42:45] offset:1360
	ds_write_b128 v151, v[46:49] offset:10064
	ds_write_b128 v151, v[50:53] offset:1632
	ds_write_b128 v151, v[54:57] offset:10336
	ds_write_b128 v151, v[58:61] offset:1904
	ds_write_b128 v151, v[62:65] offset:10608
	s_waitcnt lgkmcnt(0)
	ds_read_b32 v248, v155
	ds_read_b32 v249, v155 offset:2176
	ds_read_b32 v250, v155 offset:4352
	ds_read_b32 v251, v155 offset:6528
	ds_read_b32 v252, v155 offset:8704
	ds_read_b32 v253, v155 offset:10880
	ds_read_b32 v156, v155 offset:13056
	ds_read_b32 v157, v155 offset:15232
	s_waitcnt lgkmcnt(0)
	v_cvt_pk_bf16_f32 v146, v248, v249
	s_waitcnt lgkmcnt(0)
	v_cvt_pk_bf16_f32 v147, v250, v251
	s_waitcnt lgkmcnt(0)
	v_cvt_pk_bf16_f32 v148, v252, v253
	s_waitcnt lgkmcnt(0)
	v_cvt_pk_bf16_f32 v149, v156, v157
	ds_read_b32 v248, v155 offset:32
	ds_read_b32 v249, v155 offset:2208
	ds_read_b32 v250, v155 offset:4384
	ds_read_b32 v251, v155 offset:6560
	ds_read_b32 v252, v155 offset:8736
	ds_read_b32 v253, v155 offset:10912
	ds_read_b32 v156, v155 offset:13088
	ds_read_b32 v157, v155 offset:15264
	global_store_dwordx4 v158, v[146:149], s[6:7]
	s_waitcnt lgkmcnt(0)
	s_nop 0
	v_cvt_pk_bf16_f32 v146, v248, v249
	s_waitcnt lgkmcnt(0)
	v_cvt_pk_bf16_f32 v147, v250, v251
	s_waitcnt lgkmcnt(0)
	v_cvt_pk_bf16_f32 v148, v252, v253
	s_waitcnt lgkmcnt(0)
	v_cvt_pk_bf16_f32 v149, v156, v157
	ds_read_b32 v248, v155 offset:64
	ds_read_b32 v249, v155 offset:2240
	ds_read_b32 v250, v155 offset:4416
	ds_read_b32 v251, v155 offset:6592
	ds_read_b32 v252, v155 offset:8768
	ds_read_b32 v253, v155 offset:10944
	ds_read_b32 v156, v155 offset:13120
	ds_read_b32 v157, v155 offset:15296
	global_store_dwordx4 v158, v[146:149], s[22:23]
	s_add_u32 s22, s22, s12
	s_addc_u32 s23, s23, s13
	s_waitcnt lgkmcnt(0)
; #define GAS __attribute__((address_space(1)))
; #define LAS __attribute__((address_space(3)))
; __device__ __forceinline__ unsigned cvt_pk_bf16(float lo, float hi) { unsigned r; asm volatile("v_cvt_pk_bf16_f32 %0, %1, %2" : "=v"(r) : "v"(lo), "v"(hi)); return r; }
; #define LDS_WAIT() asm volatile("s_waitcnt lgkmcnt(0)" ::: "memory")
; __device__ __forceinline__ void p0_finish(const P0Item& it, const f32x4 (&w)[16], LAS float* scr, int lane) {
;     ...
; #pragma unroll
;     for (int j = 0; j < 8; ++j) { const int n = (lane >> 3) + 8 * j, c = lane & 7; const LAS float* sp = scr + (8 * c) * 68 + n;
;         u32x4 o; o.x = cvt_pk_bf16(sp[0 * 68], sp[1 * 68]); o.y = cvt_pk_bf16(sp[2 * 68], sp[3 * 68]); o.z = cvt_pk_bf16(sp[4 * 68], sp[5 * 68]); o.w = cvt_pk_bf16(sp[6 * 68], sp[7 * 68]);
;         *(GAS u32x4*)((char*)(it.dst + (size_t)(8 * j) * it.K) + soff) = o; }
;     LDS_WAIT(); asm volatile("" ::: "memory");
; template <class F> __device__ __forceinline__ void p0_pipe(int n, F desc, LAS float* scr, int lane) {
;     ...
;     for (int j = 0; j < n; j += 2) {
;         const bool hb_ = j + 1 < n; if (hb_) { b = desc(j + 1); p0_load(b, w1, lane); }
;         p0_finish(a, w0, scr, lane);
;         if (!hb_) break;
;         if (j + 2 < n) { a = desc(j + 2); p0_load(a, w0, lane); }
;         p0_finish(b, w1, scr, lane);
	v_cvt_pk_bf16_f32 v146, v248, v249
	s_waitcnt lgkmcnt(0)
	v_cvt_pk_bf16_f32 v147, v250, v251
	s_waitcnt lgkmcnt(0)
	v_cvt_pk_bf16_f32 v148, v252, v253
	s_waitcnt lgkmcnt(0)
	v_cvt_pk_bf16_f32 v149, v156, v157
	ds_read_b32 v248, v155 offset:96
	ds_read_b32 v249, v155 offset:2272
	ds_read_b32 v250, v155 offset:4448
	ds_read_b32 v251, v155 offset:6624
	ds_read_b32 v252, v155 offset:8800
	ds_read_b32 v253, v155 offset:10976
	ds_read_b32 v156, v155 offset:13152
	ds_read_b32 v157, v155 offset:15328
	global_store_dwordx4 v158, v[146:149], s[22:23]
	s_add_u32 s22, s22, s12
	s_addc_u32 s23, s23, s13
	s_waitcnt lgkmcnt(0)
	v_cvt_pk_bf16_f32 v146, v248, v249
	s_waitcnt lgkmcnt(0)
	v_cvt_pk_bf16_f32 v147, v250, v251
	s_waitcnt lgkmcnt(0)
	v_cvt_pk_bf16_f32 v148, v252, v253
	s_waitcnt lgkmcnt(0)
	v_cvt_pk_bf16_f32 v149, v156, v157
	ds_read_b32 v248, v155 offset:128
	ds_read_b32 v249, v155 offset:2304
	ds_read_b32 v250, v155 offset:4480
	ds_read_b32 v251, v155 offset:6656
	ds_read_b32 v252, v155 offset:8832
	ds_read_b32 v253, v155 offset:11008
	ds_read_b32 v156, v155 offset:13184
	ds_read_b32 v157, v155 offset:15360
	global_store_dwordx4 v158, v[146:149], s[22:23]
	s_add_u32 s22, s22, s12
	s_addc_u32 s23, s23, s13
	s_waitcnt lgkmcnt(0)
	v_cvt_pk_bf16_f32 v146, v248, v249
	s_waitcnt lgkmcnt(0)
	v_cvt_pk_bf16_f32 v147, v250, v251
	s_waitcnt lgkmcnt(0)
	v_cvt_pk_bf16_f32 v148, v252, v253
	s_waitcnt lgkmcnt(0)
	v_cvt_pk_bf16_f32 v149, v156, v157
	ds_read_b32 v156, v155 offset:160
	ds_read_b32 v157, v155 offset:2336
	global_store_dwordx4 v158, v[146:149], s[22:23]
	s_waitcnt lgkmcnt(0)
	v_cvt_pk_bf16_f32 v176, v156, v157
	ds_read_b32 v146, v155 offset:4512
	ds_read_b32 v147, v155 offset:6688
	s_waitcnt lgkmcnt(0)
	v_cvt_pk_bf16_f32 v177, v146, v147
	ds_read_b32 v146, v155 offset:8864
	ds_read_b32 v147, v155 offset:11040
	s_waitcnt lgkmcnt(0)
	v_cvt_pk_bf16_f32 v178, v146, v147
	v_add_u32_e32 v146, 0x600, v155
	ds_read_b32 v148, v155 offset:13216
	ds_read_b32 v149, v155 offset:15392
	s_add_u32 s22, s22, s12
	s_waitcnt lgkmcnt(0)
	v_cvt_pk_bf16_f32 v179, v148, v149
	ds_read_b32 v248, v155 offset:192
	ds_read_b32 v249, v155 offset:2368
	ds_read_b32 v250, v155 offset:4544
	ds_read_b32 v251, v155 offset:6720
	ds_read_b32 v252, v155 offset:8896
	ds_read_b32 v253, v155 offset:11072
	ds_read_b32 v148, v155 offset:13248
	ds_read_b32 v149, v155 offset:15424
	s_addc_u32 s23, s23, s13
	global_store_dwordx4 v158, v[176:179], s[22:23]
	s_add_u32 s22, s22, s12
	s_addc_u32 s23, s23, s13
	s_waitcnt lgkmcnt(0)
	v_cvt_pk_bf16_f32 v176, v248, v249
	s_waitcnt lgkmcnt(0)
	v_cvt_pk_bf16_f32 v177, v250, v251
	s_waitcnt lgkmcnt(0)
	v_cvt_pk_bf16_f32 v178, v252, v253
	s_waitcnt lgkmcnt(0)
	v_cvt_pk_bf16_f32 v179, v148, v149
	ds_read_b32 v248, v155 offset:224
	ds_read_b32 v249, v155 offset:2400
	ds_read_b32 v250, v155 offset:4576
	ds_read_b32 v251, v155 offset:6752
	ds_read_b32 v252, v155 offset:8928
	ds_read_b32 v253, v155 offset:11104
	ds_read_b32 v148, v155 offset:13280
	ds_read_b32 v149, v155 offset:15456
	v_add_u32_e32 v147, 0x200, v155
	global_store_dwordx4 v158, v[176:179], s[22:23]
	s_add_u32 s12, s22, s12
	s_addc_u32 s13, s23, s13
	s_waitcnt lgkmcnt(0)
	v_cvt_pk_bf16_f32 v176, v248, v249
	s_waitcnt lgkmcnt(0)
	v_cvt_pk_bf16_f32 v177, v250, v251
	s_waitcnt lgkmcnt(0)
	v_cvt_pk_bf16_f32 v178, v252, v253
	s_waitcnt lgkmcnt(0)
	v_cvt_pk_bf16_f32 v179, v148, v149
	global_store_dwordx4 v158, v[176:179], s[12:13]
	s_waitcnt lgkmcnt(0)
	s_cmp_gt_u32 s28, 13
	s_cselect_b64 s[12:13], -1, 0
	s_and_b64 vcc, exec, s[12:13]
	s_cbranch_vccnz .LBB0_294
	s_add_i32 s11, s24, 0xffff1000
	s_cmpk_gt_i32 s11, 0xfff
	s_mov_b64 s[22:23], -1
	s_cbranch_scc0 .LBB0_326
	s_cmpk_gt_u32 s11, 0x1fff
	s_cbranch_scc0 .LBB0_323
	s_cmpk_gt_u32 s11, 0x2fff
	s_cbranch_scc0 .LBB0_320
	s_add_i32 s0, s25, 0x400
	s_and_b32 s29, s0, 0xfc0
	s_cmpk_gt_u32 s11, 0x3fff
	s_cbranch_scc0 .LBB0_317
	s_and_b32 s0, s11, 0x7fffffc0
	s_addk_i32 s0, 0xc000
	s_lshl_b64 s[6:7], s[0:1], 14
	v_lshl_add_u64 v[2:3], v[142:143], 0, s[6:7]
	s_lshl_b32 s6, s29, 2
	s_mov_b32 s7, s1
	v_lshl_add_u64 v[2:3], v[2:3], 0, s[6:7]
	s_lshl_b32 s6, s29, 15
	v_readlane_b32 s22, v254, 13
	v_readlane_b32 s23, v254, 14
	s_add_u32 s22, s22, s6
	s_addc_u32 s23, s23, 0
	s_lshl_b64 s[6:7], s[0:1], 1
	s_add_u32 s6, s22, s6
	s_addc_u32 s7, s23, s7
	s_mov_b64 s[22:23], 0

; #define GAS __attribute__((address_space(1)))
; #define LAS __attribute__((address_space(3)))
; __device__ __forceinline__ unsigned cvt_pk_bf16(float lo, float hi) { unsigned r; asm volatile("v_cvt_pk_bf16_f32 %0, %1, %2" : "=v"(r) : "v"(lo), "v"(hi)); return r; }
; #define LDS_WAIT() asm volatile("s_waitcnt lgkmcnt(0)" ::: "memory")
; __device__ __forceinline__ void p0_finish(const P0Item& it, const f32x4 (&w)[16], LAS float* scr, int lane) {
;     ...
;     LDS_WAIT(); asm volatile("" ::: "memory");
;     const unsigned soff = (unsigned)(((lane >> 3) * it.K + 8 * (lane & 7)) * 2);
; #pragma unroll
;     for (int j = 0; j < 8; ++j) { const int n = (lane >> 3) + 8 * j, c = lane & 7; const LAS float* sp = scr + (8 * c) * 68 + n;
;         u32x4 o; o.x = cvt_pk_bf16(sp[0 * 68], sp[1 * 68]); o.y = cvt_pk_bf16(sp[2 * 68], sp[3 * 68]); o.z = cvt_pk_bf16(sp[4 * 68], sp[5 * 68]); o.w = cvt_pk_bf16(sp[6 * 68], sp[7 * 68]);
;         *(GAS u32x4*)((char*)(it.dst + (size_t)(8 * j) * it.K) + soff) = o; }
;     LDS_WAIT(); asm volatile("" ::: "memory");
; template <class F> __device__ __forceinline__ void p0_pipe(int n, F desc, LAS float* scr, int lane) {
;     ...
;     for (int j = 0; j < n; j += 2) {
;         const bool hb_ = j + 1 < n; if (hb_) { b = desc(j + 1); p0_load(b, w1, lane); }
;         p0_finish(a, w0, scr, lane);
;         if (!hb_) break;
;         if (j + 2 < n) { a = desc(j + 2); p0_load(a, w0, lane); }
;         p0_finish(b, w1, scr, lane);
.LBB0_457:
	s_or_b64 exec, exec, s[22:23]
	s_waitcnt vmcnt(0)
	ds_write_b128 v151, v[66:69] offset:10608
	s_waitcnt lgkmcnt(0)
	s_lshl_b64 s[10:11], s[10:11], 13
	s_add_u32 s10, s33, s10
	ds_read_b32 v248, v154
	ds_read_b32 v249, v154 offset:2176
	ds_read_b32 v250, v154 offset:4352
	ds_read_b32 v251, v154 offset:6528
	ds_read_b32 v252, v154 offset:8704
	ds_read_b32 v253, v154 offset:10880
	ds_read_b32 v70, v154 offset:13056
	ds_read_b32 v71, v154 offset:15232
	s_addc_u32 s11, s60, s11
	s_lshl_b64 s[8:9], s[8:9], 1
	s_waitcnt lgkmcnt(0)
	v_cvt_pk_bf16_f32 v66, v248, v249
	s_add_u32 s8, s10, s8
	s_waitcnt lgkmcnt(0)
	v_cvt_pk_bf16_f32 v67, v250, v251
	s_addc_u32 s9, s11, s9
	s_waitcnt lgkmcnt(0)
	v_cvt_pk_bf16_f32 v68, v252, v253
	s_waitcnt lgkmcnt(0)
	v_cvt_pk_bf16_f32 v69, v70, v71
	v_lshl_add_u64 v[72:73], s[8:9], 0, v[144:145]
	ds_read_b32 v248, v154 offset:32
	ds_read_b32 v249, v154 offset:2208
	ds_read_b32 v250, v154 offset:4384
	ds_read_b32 v251, v154 offset:6560
	ds_read_b32 v252, v154 offset:8736
	ds_read_b32 v253, v154 offset:10912
	ds_read_b32 v70, v154 offset:13088
	ds_read_b32 v71, v154 offset:15264
	global_store_dwordx4 v[72:73], v[66:69], off
	v_add_co_u32_e32 v74, vcc, s42, v72
	s_waitcnt lgkmcnt(0)
	v_cvt_pk_bf16_f32 v66, v248, v249
	s_waitcnt lgkmcnt(0)
	v_cvt_pk_bf16_f32 v67, v250, v251
	s_waitcnt lgkmcnt(0)
	v_cvt_pk_bf16_f32 v68, v252, v253
	s_waitcnt lgkmcnt(0)
	v_cvt_pk_bf16_f32 v69, v70, v71
	v_addc_co_u32_e32 v75, vcc, 0, v73, vcc
	ds_read_b32 v248, v154 offset:64
	ds_read_b32 v249, v154 offset:2240
	ds_read_b32 v250, v154 offset:4416
	ds_read_b32 v251, v154 offset:6592
	ds_read_b32 v252, v154 offset:8768
	ds_read_b32 v253, v154 offset:10944
	ds_read_b32 v70, v154 offset:13120
	ds_read_b32 v71, v154 offset:15296
	global_store_dwordx4 v[74:75], v[66:69], off
	v_add_co_u32_e32 v74, vcc, s43, v72
	s_waitcnt lgkmcnt(0)
	v_cvt_pk_bf16_f32 v66, v248, v249
	s_waitcnt lgkmcnt(0)
	v_cvt_pk_bf16_f32 v67, v250, v251
	s_waitcnt lgkmcnt(0)
	v_cvt_pk_bf16_f32 v68, v252, v253
	s_waitcnt lgkmcnt(0)
	v_cvt_pk_bf16_f32 v69, v70, v71
	v_addc_co_u32_e32 v75, vcc, 0, v73, vcc
	ds_read_b32 v248, v154 offset:96
	ds_read_b32 v249, v154 offset:2272
	ds_read_b32 v250, v154 offset:4448
	ds_read_b32 v251, v154 offset:6624
	ds_read_b32 v252, v154 offset:8800
	ds_read_b32 v253, v154 offset:10976
	ds_read_b32 v70, v154 offset:13152
	ds_read_b32 v71, v154 offset:15328
	global_store_dwordx4 v[74:75], v[66:69], off
	v_add_co_u32_e32 v74, vcc, s44, v72
	s_waitcnt lgkmcnt(0)
	v_cvt_pk_bf16_f32 v66, v248, v249
	s_waitcnt lgkmcnt(0)
	v_cvt_pk_bf16_f32 v67, v250, v251
	s_waitcnt lgkmcnt(0)
	v_cvt_pk_bf16_f32 v68, v252, v253
	s_waitcnt lgkmcnt(0)
	v_cvt_pk_bf16_f32 v69, v70, v71
	v_addc_co_u32_e32 v75, vcc, 0, v73, vcc
	ds_read_b32 v248, v154 offset:128
	ds_read_b32 v249, v154 offset:2304
	ds_read_b32 v250, v154 offset:4480
	ds_read_b32 v251, v154 offset:6656
	ds_read_b32 v252, v154 offset:8832
	ds_read_b32 v253, v154 offset:11008
	ds_read_b32 v70, v154 offset:13184
	ds_read_b32 v71, v154 offset:15360
	global_store_dwordx4 v[74:75], v[66:69], off
	v_add_co_u32_e32 v74, vcc, s26, v72
	s_waitcnt lgkmcnt(0)
	v_cvt_pk_bf16_f32 v66, v248, v249
	s_waitcnt lgkmcnt(0)
	v_cvt_pk_bf16_f32 v67, v250, v251
	s_waitcnt lgkmcnt(0)
	v_cvt_pk_bf16_f32 v68, v252, v253
	s_waitcnt lgkmcnt(0)
	v_cvt_pk_bf16_f32 v69, v70, v71
	v_addc_co_u32_e32 v75, vcc, 0, v73, vcc
	ds_read_b32 v248, v154 offset:160
	ds_read_b32 v249, v154 offset:2336
	ds_read_b32 v250, v154 offset:4512
	ds_read_b32 v251, v154 offset:6688
	ds_read_b32 v252, v154 offset:8864
	ds_read_b32 v253, v154 offset:11040
	ds_read_b32 v70, v154 offset:13216
	ds_read_b32 v71, v154 offset:15392
	global_store_dwordx4 v[74:75], v[66:69], off
	v_add_co_u32_e32 v74, vcc, s45, v72
	s_waitcnt lgkmcnt(0)
	v_cvt_pk_bf16_f32 v66, v248, v249
	s_waitcnt lgkmcnt(0)
	v_cvt_pk_bf16_f32 v67, v250, v251
	s_waitcnt lgkmcnt(0)
	v_cvt_pk_bf16_f32 v68, v252, v253
	s_waitcnt lgkmcnt(0)
	v_cvt_pk_bf16_f32 v69, v70, v71
	v_addc_co_u32_e32 v75, vcc, 0, v73, vcc
	ds_read_b32 v248, v154 offset:192
	ds_read_b32 v249, v154 offset:2368
	ds_read_b32 v250, v154 offset:4544
	ds_read_b32 v251, v154 offset:6720
	ds_read_b32 v252, v154 offset:8896
	ds_read_b32 v253, v154 offset:11072
	ds_read_b32 v70, v154 offset:13248
	ds_read_b32 v71, v154 offset:15424
	global_store_dwordx4 v[74:75], v[66:69], off
	v_add_co_u32_e32 v74, vcc, s46, v72
	s_waitcnt lgkmcnt(0)
	v_cvt_pk_bf16_f32 v66, v248, v249
	s_waitcnt lgkmcnt(0)
	v_cvt_pk_bf16_f32 v67, v250, v251
	s_waitcnt lgkmcnt(0)
	v_cvt_pk_bf16_f32 v68, v252, v253
	s_waitcnt lgkmcnt(0)
	v_cvt_pk_bf16_f32 v69, v70, v71
	v_addc_co_u32_e32 v75, vcc, 0, v73, vcc
	ds_read_b32 v248, v154 offset:224
	ds_read_b32 v249, v154 offset:2400
	ds_read_b32 v250, v154 offset:4576
	ds_read_b32 v251, v154 offset:6752
	ds_read_b32 v252, v154 offset:8928
	ds_read_b32 v253, v154 offset:11104
	ds_read_b32 v70, v154 offset:13280
	ds_read_b32 v71, v154 offset:15456
	global_store_dwordx4 v[74:75], v[66:69], off
	v_add_co_u32_e32 v72, vcc, 0x70000, v72
	s_waitcnt lgkmcnt(0)
	v_cvt_pk_bf16_f32 v66, v248, v249
	s_waitcnt lgkmcnt(0)
	v_cvt_pk_bf16_f32 v67, v250, v251
	v_addc_co_u32_e32 v73, vcc, 0, v73, vcc
	s_waitcnt lgkmcnt(0)
	v_cvt_pk_bf16_f32 v68, v252, v253
	s_waitcnt lgkmcnt(0)
	v_cvt_pk_bf16_f32 v69, v70, v71
	global_store_dwordx4 v[72:73], v[66:69], off
	s_waitcnt lgkmcnt(0)
	s_add_i32 s40, s40, 2
	s_andn2_b64 vcc, exec, s[12:13]
	s_addk_i32 s41, 0x1000
	s_cbranch_vccz .LBB0_468

; #define GAS __attribute__((address_space(1)))
; #define LAS __attribute__((address_space(3)))
; __device__ __forceinline__ unsigned cvt_pk_bf16(float lo, float hi) { unsigned r; asm volatile("v_cvt_pk_bf16_f32 %0, %1, %2" : "=v"(r) : "v"(lo), "v"(hi)); return r; }
; #define LDS_WAIT() asm volatile("s_waitcnt lgkmcnt(0)" ::: "memory")
; __device__ __forceinline__ void p0_finish(const P0Item& it, const f32x4 (&w)[16], LAS float* scr, int lane) {
;     ...
;     LDS_WAIT(); asm volatile("" ::: "memory");
;     const unsigned soff = (unsigned)(((lane >> 3) * it.K + 8 * (lane & 7)) * 2);
; #pragma unroll
;     for (int j = 0; j < 8; ++j) { const int n = (lane >> 3) + 8 * j, c = lane & 7; const LAS float* sp = scr + (8 * c) * 68 + n;
;         u32x4 o; o.x = cvt_pk_bf16(sp[0 * 68], sp[1 * 68]); o.y = cvt_pk_bf16(sp[2 * 68], sp[3 * 68]); o.z = cvt_pk_bf16(sp[4 * 68], sp[5 * 68]); o.w = cvt_pk_bf16(sp[6 * 68], sp[7 * 68]);
;         *(GAS u32x4*)((char*)(it.dst + (size_t)(8 * j) * it.K) + soff) = o; }
;     LDS_WAIT(); asm volatile("" ::: "memory");
; template <class F> __device__ __forceinline__ void p0_pipe(int n, F desc, LAS float* scr, int lane) {
;     ...
;     for (int j = 0; j < n; j += 2) {
;         const bool hb_ = j + 1 < n; if (hb_) { b = desc(j + 1); p0_load(b, w1, lane); }
;         p0_finish(a, w0, scr, lane);
;         if (!hb_) break;
;         if (j + 2 < n) { a = desc(j + 2); p0_load(a, w0, lane); }
;         p0_finish(b, w1, scr, lane);
.LBB0_462:
	s_or_b64 exec, exec, s[12:13]
	ds_write_b128 v151, v[130:133] offset:10608
	s_waitcnt lgkmcnt(0)
	ds_read_b32 v248, v154
	ds_read_b32 v249, v154 offset:2176
	ds_read_b32 v250, v154 offset:4352
	ds_read_b32 v251, v154 offset:6528
	ds_read_b32 v252, v154 offset:8704
	ds_read_b32 v253, v154 offset:10880
	ds_read_b32 v132, v154 offset:13056
	ds_read_b32 v133, v154 offset:15232
	s_waitcnt lgkmcnt(0)
	v_cvt_pk_bf16_f32 v156, v248, v249
	v_add_u32_e32 v130, 0x400, v154
	s_waitcnt lgkmcnt(0)
	v_cvt_pk_bf16_f32 v157, v250, v251
	s_waitcnt lgkmcnt(0)
	v_cvt_pk_bf16_f32 v158, v252, v253
	s_waitcnt lgkmcnt(0)
	v_cvt_pk_bf16_f32 v159, v132, v133
	ds_read_b32 v248, v154 offset:32
	ds_read_b32 v249, v154 offset:2208
	ds_read_b32 v250, v154 offset:4384
	ds_read_b32 v251, v154 offset:6560
	ds_read_b32 v252, v154 offset:8736
	ds_read_b32 v253, v154 offset:10912
	ds_read_b32 v132, v154 offset:13088
	ds_read_b32 v133, v154 offset:15264
	v_lshl_add_u64 v[160:161], s[0:1], 0, v[144:145]
	global_store_dwordx4 v[160:161], v[156:159], off
	v_add_co_u32_e32 v162, vcc, s42, v160
	s_waitcnt lgkmcnt(0)
	v_cvt_pk_bf16_f32 v156, v248, v249
	s_waitcnt lgkmcnt(0)
	v_cvt_pk_bf16_f32 v157, v250, v251
	s_waitcnt lgkmcnt(0)
	v_cvt_pk_bf16_f32 v158, v252, v253
	s_waitcnt lgkmcnt(0)
	v_cvt_pk_bf16_f32 v159, v132, v133
	ds_read_b32 v248, v154 offset:64
	ds_read_b32 v249, v154 offset:2240
	ds_read_b32 v250, v154 offset:4416
	ds_read_b32 v251, v154 offset:6592
	ds_read_b32 v252, v154 offset:8768
	ds_read_b32 v253, v154 offset:10944
	ds_read_b32 v132, v154 offset:13120
	ds_read_b32 v133, v154 offset:15296
	v_addc_co_u32_e32 v163, vcc, 0, v161, vcc
	global_store_dwordx4 v[162:163], v[156:159], off
	v_add_co_u32_e32 v162, vcc, s43, v160
	s_waitcnt lgkmcnt(0)
	v_cvt_pk_bf16_f32 v156, v248, v249
	s_waitcnt lgkmcnt(0)
	v_cvt_pk_bf16_f32 v157, v250, v251
	s_waitcnt lgkmcnt(0)
	v_cvt_pk_bf16_f32 v158, v252, v253
	s_waitcnt lgkmcnt(0)
	v_cvt_pk_bf16_f32 v159, v132, v133
	ds_read_b32 v248, v154 offset:96
	ds_read_b32 v249, v154 offset:2272
	ds_read_b32 v250, v154 offset:4448
	ds_read_b32 v251, v154 offset:6624
	ds_read_b32 v252, v154 offset:8800
	ds_read_b32 v253, v154 offset:10976
	ds_read_b32 v132, v154 offset:13152
	ds_read_b32 v133, v154 offset:15328
	v_addc_co_u32_e32 v163, vcc, 0, v161, vcc
	global_store_dwordx4 v[162:163], v[156:159], off
	v_add_co_u32_e32 v162, vcc, s44, v160
	s_waitcnt lgkmcnt(0)
	v_cvt_pk_bf16_f32 v156, v248, v249
	s_waitcnt lgkmcnt(0)
	v_cvt_pk_bf16_f32 v157, v250, v251
	s_waitcnt lgkmcnt(0)
	v_cvt_pk_bf16_f32 v158, v252, v253
	s_waitcnt lgkmcnt(0)
	v_cvt_pk_bf16_f32 v159, v132, v133
	ds_read_b32 v248, v154 offset:128
	ds_read_b32 v249, v154 offset:2304
	ds_read_b32 v250, v154 offset:4480
	ds_read_b32 v251, v154 offset:6656
	ds_read_b32 v252, v154 offset:8832
	ds_read_b32 v253, v154 offset:11008
	ds_read_b32 v132, v154 offset:13184
	ds_read_b32 v133, v154 offset:15360
	v_addc_co_u32_e32 v163, vcc, 0, v161, vcc
	global_store_dwordx4 v[162:163], v[156:159], off
	v_add_co_u32_e32 v162, vcc, s26, v160
	s_waitcnt lgkmcnt(0)
	v_cvt_pk_bf16_f32 v156, v248, v249
	s_waitcnt lgkmcnt(0)
	v_cvt_pk_bf16_f32 v157, v250, v251
	s_waitcnt lgkmcnt(0)
	v_cvt_pk_bf16_f32 v158, v252, v253
	s_waitcnt lgkmcnt(0)
	v_cvt_pk_bf16_f32 v159, v132, v133
	ds_read_b32 v248, v154 offset:160
	ds_read_b32 v249, v154 offset:2336
	ds_read_b32 v250, v154 offset:4512
	ds_read_b32 v251, v154 offset:6688
	ds_read_b32 v252, v154 offset:8864
	ds_read_b32 v253, v154 offset:11040
	ds_read_b32 v132, v154 offset:13216
	ds_read_b32 v133, v154 offset:15392
	v_addc_co_u32_e32 v163, vcc, 0, v161, vcc
	global_store_dwordx4 v[162:163], v[156:159], off
	v_add_u32_e32 v131, 0x600, v154
	v_add_co_u32_e32 v162, vcc, s45, v160
	s_waitcnt lgkmcnt(0)
	v_cvt_pk_bf16_f32 v156, v248, v249
	s_waitcnt lgkmcnt(0)
	v_cvt_pk_bf16_f32 v157, v250, v251
	s_waitcnt lgkmcnt(0)
	v_cvt_pk_bf16_f32 v158, v252, v253
	s_waitcnt lgkmcnt(0)
	v_cvt_pk_bf16_f32 v159, v132, v133
	ds_read_b32 v132, v154 offset:192
	ds_read_b32 v133, v154 offset:2368
	v_addc_co_u32_e32 v163, vcc, 0, v161, vcc
	global_store_dwordx4 v[162:163], v[156:159], off
	v_add_co_u32_e32 v164, vcc, s46, v160
	s_waitcnt lgkmcnt(0)
	v_cvt_pk_bf16_f32 v156, v132, v133
	ds_read_b32 v132, v154 offset:4544
	ds_read_b32 v133, v154 offset:6720
	s_waitcnt lgkmcnt(0)
	v_cvt_pk_bf16_f32 v157, v132, v133
	ds_read_b32 v132, v154 offset:8896
	ds_read_b32 v133, v154 offset:11072
	s_waitcnt lgkmcnt(0)
	v_cvt_pk_bf16_f32 v158, v132, v133
	ds_read_b32 v162, v154 offset:13248
	ds_read_b32 v163, v154 offset:15424
	v_add_u32_e32 v132, 0x200, v154
	s_waitcnt lgkmcnt(0)
	v_cvt_pk_bf16_f32 v159, v162, v163
	v_addc_co_u32_e32 v165, vcc, 0, v161, vcc
	ds_read_b32 v248, v154 offset:224
	ds_read_b32 v249, v154 offset:2400
	ds_read_b32 v250, v154 offset:4576
	ds_read_b32 v251, v154 offset:6752
	ds_read_b32 v252, v154 offset:8928
	ds_read_b32 v253, v154 offset:11104
	ds_read_b32 v162, v154 offset:13280
	ds_read_b32 v163, v154 offset:15456
	global_store_dwordx4 v[164:165], v[156:159], off
	v_add_co_u32_e32 v160, vcc, 0x70000, v160
	s_waitcnt lgkmcnt(0)
	v_cvt_pk_bf16_f32 v156, v248, v249
	s_waitcnt lgkmcnt(0)
	v_cvt_pk_bf16_f32 v157, v250, v251
	v_addc_co_u32_e32 v161, vcc, 0, v161, vcc
	s_waitcnt lgkmcnt(0)
	v_cvt_pk_bf16_f32 v158, v252, v253
	s_waitcnt lgkmcnt(0)
	v_cvt_pk_bf16_f32 v159, v162, v163
	global_store_dwordx4 v[160:161], v[156:159], off
	s_waitcnt lgkmcnt(0)
	s_cmp_gt_u32 s40, 5
	s_cselect_b64 s[12:13], -1, 0
	s_and_b64 vcc, exec, s[12:13]
	s_cbranch_vccz .LBB0_465
	s_and_saveexec_b64 s[22:23], s[4:5]
	s_xor_b64 s[22:23], exec, s[22:23]
	s_cbranch_execnz .LBB0_466
